# remove inline-asm pad s_nop 0 between v_add/v_cvt_pk in attention loops (186 nops)
# speedup vs baseline: 1.0006x; 1.0006x over previous
.LBB0_340:
	s_add_i32 s22, s20, 0xffffc000
	s_and_b32 s22, s22, 0xc000
	v_add_u32_e32 v96, s22, v173
	ds_read_b128 v[164:167], v96 offset:4096
	ds_read_b128 v[182:185], v96 offset:4608
	ds_read_b128 v[186:189], v96 offset:6144
	ds_read_b128 v[190:193], v96 offset:6656
	s_lshl_b32 s16, s16, 14
	s_add_i32 s16, s16, 0
	v_add_f32_e32 v96, v177, v80
	v_cvt_pk_bf16_f32 v160, v80, v79
	v_cvt_pk_bf16_f32 v161, v88, v87
	s_waitcnt lgkmcnt(7)
	v_mfma_f32_32x32x16_bf16 v[112:127], v[156:159], v[140:143], 0
	v_add_f32_e32 v96, v96, v79
	v_add_f32_e32 v96, v96, v88
	v_add_f32_e32 v96, v96, v87
	v_add_f32_e32 v79, v96, v82
	v_cvt_pk_bf16_f32 v162, v82, v83
	v_cvt_pk_bf16_f32 v163, v92, v91
	s_waitcnt lgkmcnt(6)
	v_mfma_f32_32x32x16_bf16 v[96:111], v[148:151], v[140:143], 0
	v_add_f32_e32 v79, v79, v83
	v_add_f32_e32 v79, v79, v92
	v_add_f32_e32 v79, v79, v91
	v_add_f32_e32 v79, v79, v76
	s_waitcnt lgkmcnt(5)
	v_mfma_f32_32x32x16_bf16 v[112:127], v[152:155], v[136:139], v[112:127]
	v_add_f32_e32 v79, v79, v75
	v_cvt_pk_bf16_f32 v148, v76, v75
	v_cvt_pk_bf16_f32 v149, v86, v85
	v_add_f32_e32 v79, v79, v86
	v_add_f32_e32 v79, v79, v85
	v_add_f32_e32 v75, v79, v74
	s_waitcnt lgkmcnt(4)
	v_mfma_f32_32x32x16_bf16 v[96:111], v[144:147], v[136:139], v[96:111]
	v_add_f32_e32 v75, v75, v93
	v_cvt_pk_bf16_f32 v150, v74, v93
	v_cvt_pk_bf16_f32 v151, v94, v95
	v_add_f32_e32 v75, v75, v94
	v_add_f32_e32 v75, v75, v95
	v_add_f32_e32 v74, v75, v84
	s_waitcnt lgkmcnt(3)
	v_mfma_f32_32x32x16_bf16 v[112:127], v[164:167], v[132:135], v[112:127]
	v_add_f32_e32 v74, v74, v81
	v_add_f32_e32 v74, v74, v90
	v_add_f32_e32 v76, v74, v89
	v_cvt_pk_bf16_f32 v74, v84, v81
	v_cvt_pk_bf16_f32 v75, v90, v89
	v_add_f32_e32 v76, v76, v72
	s_waitcnt lgkmcnt(2)
	v_mfma_f32_32x32x16_bf16 v[96:111], v[182:185], v[132:135], v[96:111]
	v_add_f32_e32 v76, v76, v73
	v_add_f32_e32 v76, v76, v78
	v_add_f32_e32 v82, v76, v77
	v_cvt_pk_bf16_f32 v76, v72, v73
	v_cvt_pk_bf16_f32 v77, v78, v77
	v_add_u32_e32 v83, s16, v170
	v_add_u32_e32 v144, s16, v171
	ds_read_b64_tr_b16 v[78:79], v83
	ds_read_b64_tr_b16 v[80:81], v144
	ds_read_b64_tr_b16 v[86:87], v144 offset:512
	ds_read_b64_tr_b16 v[84:85], v83 offset:512
	v_add_f32_e32 v72, v82, v68
	s_waitcnt lgkmcnt(5)
	v_mfma_f32_32x32x16_bf16 v[112:127], v[186:189], v[128:131], v[112:127]
	v_add_f32_e32 v72, v72, v69
	v_cvt_pk_bf16_f32 v68, v68, v69
	v_cvt_pk_bf16_f32 v69, v70, v71
	v_add_f32_e32 v72, v72, v70
	v_add_f32_e32 v72, v72, v71
	v_add_f32_e32 v70, v72, v64
	s_waitcnt lgkmcnt(4)
	v_mfma_f32_32x32x16_bf16 v[96:111], v[190:193], v[128:131], v[96:111]
	v_add_f32_e32 v70, v70, v65
	v_add_f32_e32 v70, v70, v66
	v_add_f32_e32 v72, v70, v67
	v_cvt_pk_bf16_f32 v70, v64, v65
	v_cvt_pk_bf16_f32 v71, v66, v67
	s_add_i32 s16, s20, 0x8000
	s_and_b32 s23, s16, 0xc000
	s_add_i32 s23, s23, s46
	s_add_i32 s24, s23, 0
	s_add_u32 s25, s0, s49
	s_addc_u32 s26, s1, 0
	s_add_u32 s28, s25, 0x9d08000
	s_addc_u32 s29, s26, 0
	s_mov_b32 s27, m0
	s_mov_b32 m0, s24
	s_nop 0
	global_load_lds_dwordx4 v172, s[28:29]
	s_mov_b32 m0, s27
	s_add_u32 s28, s25, 0x9e10000
	s_addc_u32 s29, s26, 0
	s_add_i32 s24, 0, 0x2000
	s_add_i32 s23, s23, s24
	s_mov_b32 s27, m0
	s_mov_b32 m0, s23
	s_nop 0
	global_load_lds_dwordx4 v172, s[28:29]
	s_mov_b32 m0, s27
	s_lshl_b32 s23, s19, 14
	s_add_i32 s23, s23, s17
	s_add_i32 s29, s23, 0
	s_add_u32 s27, s14, s49
	s_addc_u32 s28, s15, 0
	s_add_u32 s30, s27, 0xae08000
	s_addc_u32 s31, s28, 0
	s_mov_b32 s52, m0
	s_mov_b32 m0, s29
	s_nop 0
	global_load_lds_dwordx4 v172, s[30:31]
	s_mov_b32 m0, s52
	s_add_u32 s30, s27, 0xae0a000
	s_addc_u32 s31, s28, 0
	s_add_i32 s23, s23, s24
	s_mov_b32 s29, m0
	s_mov_b32 m0, s23
	s_nop 0
	global_load_lds_dwordx4 v172, s[30:31]
	s_mov_b32 m0, s29
	v_add_f32_e32 v82, v174, v72
	s_waitcnt lgkmcnt(2)
	v_mfma_f32_32x32x16_bf16 v[48:63], v[78:81], v[160:163], v[48:63]
	ds_read_b64_tr_b16 v[64:65], v83 offset:1024
	ds_read_b64_tr_b16 v[66:67], v144 offset:1024
	v_exp_f32_e32 v156, v112
	v_exp_f32_e32 v157, v113
	s_waitcnt lgkmcnt(2)
	v_mfma_f32_32x32x16_bf16 v[32:47], v[84:87], v[160:163], v[32:47]
	ds_read_b64_tr_b16 v[78:79], v83 offset:1536
	ds_read_b64_tr_b16 v[80:81], v144 offset:1536
	v_exp_f32_e32 v158, v114
	v_exp_f32_e32 v159, v115
	s_waitcnt lgkmcnt(2)
	v_mfma_f32_32x32x16_bf16 v[16:31], v[64:67], v[160:163], v[16:31]
	ds_read_b64_tr_b16 v[84:85], v83 offset:4096
	ds_read_b64_tr_b16 v[86:87], v144 offset:4096
	v_exp_f32_e32 v164, v116
	v_exp_f32_e32 v165, v117
	s_waitcnt lgkmcnt(2)
	v_mfma_f32_32x32x16_bf16 v[0:15], v[78:81], v[160:163], v[0:15]
	ds_read_b64_tr_b16 v[88:89], v83 offset:4608
	ds_read_b64_tr_b16 v[90:91], v144 offset:4608
	v_exp_f32_e32 v160, v118
	v_exp_f32_e32 v161, v119
	s_and_b32 s23, s20, 0xc000
	v_add_u32_e32 v152, s23, v173
	ds_read_b128 v[92:95], v152
	ds_read_b128 v[78:81], v152 offset:512
	s_waitcnt lgkmcnt(4)
	v_mfma_f32_32x32x16_bf16 v[48:63], v[84:87], v[148:151], v[48:63]
	ds_read_b64_tr_b16 v[112:113], v83 offset:5120
	ds_read_b64_tr_b16 v[114:115], v144 offset:5120
	v_exp_f32_e32 v162, v120
	v_exp_f32_e32 v163, v121
	ds_read_b128 v[84:87], v152 offset:2048
	ds_read_b128 v[64:67], v152 offset:2560
	s_waitcnt lgkmcnt(6)
	v_mfma_f32_32x32x16_bf16 v[32:47], v[88:91], v[148:151], v[32:47]
	ds_read_b64_tr_b16 v[116:117], v83 offset:5632
	ds_read_b64_tr_b16 v[118:119], v144 offset:5632
	v_exp_f32_e32 v166, v122
	v_exp_f32_e32 v167, v123
	s_waitcnt lgkmcnt(4)
	v_mfma_f32_32x32x16_bf16 v[16:31], v[112:115], v[148:151], v[16:31]
	ds_read_b64_tr_b16 v[88:89], v83 offset:8192
	ds_read_b64_tr_b16 v[90:91], v144 offset:8192
	v_exp_f32_e32 v174, v124
	v_exp_f32_e32 v175, v125
	s_waitcnt lgkmcnt(2)
; #define AT_WAIT_BAR(N) asm volatile("s_waitcnt vmcnt(" #N ") lgkmcnt(0)\n\ts_barrier" ::: "memory")
; #define AT_ROT() do { sl_prev = sl_cur; sl_cur = sl_next; sl_next = (sl_next == 2) ? 0 : sl_next + 1; } while (0)
; __device__ __forceinline__ void attn_unit(LAS unsigned char* lds, const bf16_t* Qb, const bf16_t* Kb, const bf16_t* Vb, bf16_t* mix,
;                                           int b, int head, int qbase  , float lam, float post_scale, const float* subg) {
;     ...
;     int t = 1;
;     for (; t + 5 < NT; t += 2) {
;         AT_STEP(pB0, pB1, pA0, pA1, t, true, true, true);     AT_WAIT_BAR(4); AT_ROT();
;         AT_STEP(pA0, pA1, pB0, pB1, t + 1, true, true, true); AT_WAIT_BAR(4); AT_ROT();
	v_mfma_f32_32x32x16_bf16 v[0:15], v[116:119], v[148:151], v[0:15]
	ds_read_b64_tr_b16 v[112:113], v83 offset:8704
	ds_read_b64_tr_b16 v[114:115], v144 offset:8704
	v_exp_f32_e32 v176, v126
	v_exp_f32_e32 v182, v127
	s_waitcnt lgkmcnt(2)
	v_mfma_f32_32x32x16_bf16 v[48:63], v[88:91], v[74:77], v[48:63]
	ds_read_b64_tr_b16 v[116:117], v83 offset:9216
	ds_read_b64_tr_b16 v[118:119], v144 offset:9216
	v_exp_f32_e32 v183, v96
	v_exp_f32_e32 v184, v97
	s_waitcnt lgkmcnt(2)
	v_mfma_f32_32x32x16_bf16 v[32:47], v[112:115], v[74:77], v[32:47]
	ds_read_b64_tr_b16 v[88:89], v83 offset:9728
	ds_read_b64_tr_b16 v[90:91], v144 offset:9728
	v_exp_f32_e32 v185, v98
	v_exp_f32_e32 v186, v99
	s_waitcnt lgkmcnt(2)
	v_mfma_f32_32x32x16_bf16 v[16:31], v[116:119], v[74:77], v[16:31]
	ds_read_b64_tr_b16 v[96:97], v83 offset:12288
	ds_read_b64_tr_b16 v[98:99], v144 offset:12288
	v_exp_f32_e32 v187, v100
	v_exp_f32_e32 v188, v101
	s_waitcnt lgkmcnt(2)
	v_mfma_f32_32x32x16_bf16 v[0:15], v[88:91], v[74:77], v[0:15]
	ds_read_b64_tr_b16 v[112:113], v83 offset:12800
	ds_read_b64_tr_b16 v[114:115], v144 offset:12800
	v_exp_f32_e32 v76, v102
	v_exp_f32_e32 v77, v103
	s_waitcnt lgkmcnt(2)
	v_mfma_f32_32x32x16_bf16 v[48:63], v[96:99], v[68:71], v[48:63]
	ds_read_b64_tr_b16 v[72:73], v83 offset:13312
	ds_read_b64_tr_b16 v[74:75], v144 offset:13312
	v_exp_f32_e32 v189, v104
	v_exp_f32_e32 v190, v105
	s_waitcnt lgkmcnt(2)
	v_mfma_f32_32x32x16_bf16 v[32:47], v[112:115], v[68:71], v[32:47]
	ds_read_b64_tr_b16 v[88:89], v83 offset:13824
	ds_read_b64_tr_b16 v[90:91], v144 offset:13824
	v_exp_f32_e32 v83, v106
	v_exp_f32_e32 v191, v107
	s_waitcnt lgkmcnt(2)
	v_mfma_f32_32x32x16_bf16 v[16:31], v[72:75], v[68:71], v[16:31]
	v_exp_f32_e32 v192, v108
	v_exp_f32_e32 v193, v109
	s_waitcnt lgkmcnt(0)
	v_mfma_f32_32x32x16_bf16 v[0:15], v[88:91], v[68:71], v[0:15]
	v_exp_f32_e32 v194, v110
	v_exp_f32_e32 v195, v111
	s_waitcnt vmcnt(4) lgkmcnt(0)
	s_barrier
	s_add_i32 s23, s19, 1
	s_cmp_lg_u32 s19, 2
	s_cselect_b32 s23, s23, 0
	ds_read_b128 v[88:91], v152 offset:4096
	ds_read_b128 v[144:147], v152 offset:4608
	ds_read_b128 v[148:151], v152 offset:6144
	ds_read_b128 v[152:155], v152 offset:6656
	s_lshl_b32 s21, s21, 14
	s_add_i32 s21, s21, 0
	v_add_f32_e32 v68, v177, v156
	v_mfma_f32_32x32x16_bf16 v[112:127], v[92:95], v[140:143], 0
	v_add_f32_e32 v68, v68, v157
	v_cvt_pk_bf16_f32 v72, v156, v157
	v_cvt_pk_bf16_f32 v73, v158, v159
	v_add_f32_e32 v68, v68, v158
	v_add_f32_e32 v68, v68, v159
	v_add_f32_e32 v68, v68, v164
	v_cvt_pk_bf16_f32 v74, v164, v165
	v_cvt_pk_bf16_f32 v75, v160, v161
	v_mfma_f32_32x32x16_bf16 v[96:111], v[78:81], v[140:143], 0
	v_add_f32_e32 v68, v68, v165
	v_add_f32_e32 v68, v68, v160
	v_add_f32_e32 v68, v68, v161
	v_add_f32_e32 v68, v68, v162
	v_mfma_f32_32x32x16_bf16 v[112:127], v[84:87], v[136:139], v[112:127]
	v_add_f32_e32 v68, v68, v163
	v_add_f32_e32 v68, v68, v166
	v_add_f32_e32 v70, v68, v167
	v_cvt_pk_bf16_f32 v68, v162, v163
	v_cvt_pk_bf16_f32 v69, v166, v167
	v_mfma_f32_32x32x16_bf16 v[96:111], v[64:67], v[136:139], v[96:111]
	v_add_f32_e32 v64, v70, v174
	v_cvt_pk_bf16_f32 v70, v174, v175
	v_cvt_pk_bf16_f32 v71, v176, v182
	v_add_f32_e32 v64, v64, v175
	v_add_f32_e32 v64, v64, v176
	v_add_f32_e32 v64, v64, v182
	v_add_f32_e32 v64, v64, v183
	s_waitcnt lgkmcnt(3)
	v_mfma_f32_32x32x16_bf16 v[112:127], v[88:91], v[132:135], v[112:127]
	v_add_f32_e32 v64, v64, v184
	v_add_f32_e32 v64, v64, v185
	v_add_f32_e32 v66, v64, v186
	v_cvt_pk_bf16_f32 v64, v183, v184
	v_cvt_pk_bf16_f32 v65, v185, v186
	v_add_f32_e32 v66, v66, v187
	s_waitcnt lgkmcnt(2)
	v_mfma_f32_32x32x16_bf16 v[96:111], v[144:147], v[132:135], v[96:111]
	v_add_f32_e32 v66, v66, v188
	v_add_f32_e32 v66, v66, v76
	v_add_f32_e32 v80, v66, v77
	v_cvt_pk_bf16_f32 v66, v187, v188
	v_cvt_pk_bf16_f32 v67, v76, v77
	v_add_u32_e32 v175, s21, v170
	v_add_u32_e32 v176, s21, v171
	ds_read_b64_tr_b16 v[76:77], v175
	ds_read_b64_tr_b16 v[78:79], v176
	ds_read_b64_tr_b16 v[86:87], v176 offset:512
	ds_read_b64_tr_b16 v[84:85], v175 offset:512
	v_add_f32_e32 v80, v80, v189
	s_waitcnt lgkmcnt(5)
	v_mfma_f32_32x32x16_bf16 v[112:127], v[148:151], v[128:131], v[112:127]
	v_add_f32_e32 v80, v80, v190
	v_cvt_pk_bf16_f32 v160, v189, v190
	v_cvt_pk_bf16_f32 v161, v83, v191
	v_add_f32_e32 v80, v80, v83
	v_add_f32_e32 v80, v80, v191
	v_add_f32_e32 v80, v80, v192
	s_waitcnt lgkmcnt(4)
; #define AT_WAIT_BAR(N) asm volatile("s_waitcnt vmcnt(" #N ") lgkmcnt(0)\n\ts_barrier" ::: "memory")
; #define AT_ROT() do { sl_prev = sl_cur; sl_cur = sl_next; sl_next = (sl_next == 2) ? 0 : sl_next + 1; } while (0)
; __device__ __forceinline__ void attn_unit(LAS unsigned char* lds, const bf16_t* Qb, const bf16_t* Kb, const bf16_t* Vb, bf16_t* mix,
;                                           int b, int head, int qbase  , float lam, float post_scale, const float* subg) {
;     ...
;     int t = 1;
;     for (; t + 5 < NT; t += 2) {
;         AT_STEP(pB0, pB1, pA0, pA1, t, true, true, true);     AT_WAIT_BAR(4); AT_ROT();
;         AT_STEP(pA0, pA1, pB0, pB1, t + 1, true, true, true); AT_WAIT_BAR(4); AT_ROT();
;     }
	v_mfma_f32_32x32x16_bf16 v[96:111], v[152:155], v[128:131], v[96:111]
	v_add_f32_e32 v80, v80, v193
	v_cvt_pk_bf16_f32 v162, v192, v193
	v_cvt_pk_bf16_f32 v163, v194, v195
	v_add_f32_e32 v80, v80, v194
	v_add_f32_e32 v80, v80, v195
	s_add_i32 s21, s22, s46
	s_add_i32 s22, s21, 0
	s_add_u32 s30, s25, 0x9d0a000
	s_addc_u32 s31, s26, 0
	s_mov_b32 s29, m0
	s_mov_b32 m0, s22
	s_nop 0
	global_load_lds_dwordx4 v172, s[30:31]
	s_mov_b32 m0, s29
	s_add_u32 s30, s25, 0x9e12000
	s_addc_u32 s31, s26, 0
	s_add_i32 s21, s21, s24
	s_mov_b32 s22, m0
	s_mov_b32 m0, s21
	s_nop 0
	global_load_lds_dwordx4 v172, s[30:31]
	s_mov_b32 m0, s22
	s_lshl_b32 s21, s23, 14
	s_add_i32 s21, s21, s17
	s_add_i32 s22, s21, 0
	s_add_u32 s30, s27, 0xae0c000
	s_addc_u32 s31, s28, 0
	s_mov_b32 s25, m0
	s_mov_b32 m0, s22
	s_nop 0
	global_load_lds_dwordx4 v172, s[30:31]
	s_mov_b32 m0, s25
	s_add_u32 s26, s27, 0xae0e000
	s_addc_u32 s27, s28, 0
	s_add_i32 s21, s21, s24
	s_mov_b32 s22, m0
	s_mov_b32 m0, s21
	s_nop 0
	global_load_lds_dwordx4 v172, s[26:27]
	s_mov_b32 m0, s22
	v_add_f32_e32 v174, v82, v80
	s_waitcnt lgkmcnt(2)
	v_mfma_f32_32x32x16_bf16 v[48:63], v[76:79], v[72:75], v[48:63]
	ds_read_b64_tr_b16 v[90:91], v175 offset:1024
	ds_read_b64_tr_b16 v[92:93], v176 offset:1024
	v_exp_f32_e32 v80, v112
	v_exp_f32_e32 v79, v113
	s_waitcnt lgkmcnt(2)
	v_mfma_f32_32x32x16_bf16 v[32:47], v[84:87], v[72:75], v[32:47]
	ds_read_b64_tr_b16 v[144:145], v175 offset:1536
	ds_read_b64_tr_b16 v[146:147], v176 offset:1536
	v_exp_f32_e32 v88, v114
	v_exp_f32_e32 v87, v115
	s_waitcnt lgkmcnt(2)
	v_mfma_f32_32x32x16_bf16 v[16:31], v[90:93], v[72:75], v[16:31]
	ds_read_b64_tr_b16 v[112:113], v175 offset:4096
	ds_read_b64_tr_b16 v[114:115], v176 offset:4096
	v_exp_f32_e32 v82, v116
	v_exp_f32_e32 v83, v117
	s_waitcnt lgkmcnt(2)
	v_mfma_f32_32x32x16_bf16 v[0:15], v[144:147], v[72:75], v[0:15]
	ds_read_b64_tr_b16 v[164:165], v175 offset:4608
	ds_read_b64_tr_b16 v[166:167], v176 offset:4608
	v_exp_f32_e32 v92, v118
	v_exp_f32_e32 v91, v119
	s_addk_i32 s20, 0x4000
	s_and_b32 s20, s20, 0xc000
	v_add_u32_e32 v72, s20, v173
	ds_read_b128 v[156:159], v72
	ds_read_b128 v[148:151], v72 offset:512
	s_waitcnt lgkmcnt(4)
	v_mfma_f32_32x32x16_bf16 v[48:63], v[112:115], v[68:71], v[48:63]
	ds_read_b64_tr_b16 v[116:117], v175 offset:5120
	ds_read_b64_tr_b16 v[118:119], v176 offset:5120
	v_exp_f32_e32 v76, v120
	v_exp_f32_e32 v75, v121
	ds_read_b128 v[152:155], v72 offset:2048
	ds_read_b128 v[144:147], v72 offset:2560
	s_waitcnt lgkmcnt(6)
	v_mfma_f32_32x32x16_bf16 v[32:47], v[164:167], v[68:71], v[32:47]
	ds_read_b64_tr_b16 v[112:113], v175 offset:5632
	ds_read_b64_tr_b16 v[114:115], v176 offset:5632
	v_exp_f32_e32 v86, v122
	v_exp_f32_e32 v85, v123
	s_waitcnt lgkmcnt(4)
	v_mfma_f32_32x32x16_bf16 v[16:31], v[116:119], v[68:71], v[16:31]
	ds_read_b64_tr_b16 v[120:121], v175 offset:8192
	ds_read_b64_tr_b16 v[122:123], v176 offset:8192
	v_exp_f32_e32 v74, v124
	v_exp_f32_e32 v93, v125
	s_waitcnt lgkmcnt(2)
	v_mfma_f32_32x32x16_bf16 v[0:15], v[112:115], v[68:71], v[0:15]
	ds_read_b64_tr_b16 v[116:117], v175 offset:8704
	ds_read_b64_tr_b16 v[118:119], v176 offset:8704
	v_exp_f32_e32 v94, v126
	v_exp_f32_e32 v95, v127
	s_waitcnt lgkmcnt(2)
	v_mfma_f32_32x32x16_bf16 v[48:63], v[120:123], v[64:67], v[48:63]
	ds_read_b64_tr_b16 v[68:69], v175 offset:9216
	ds_read_b64_tr_b16 v[70:71], v176 offset:9216
	v_exp_f32_e32 v84, v96
	v_exp_f32_e32 v81, v97
	s_waitcnt lgkmcnt(2)
	v_mfma_f32_32x32x16_bf16 v[32:47], v[116:119], v[64:67], v[32:47]
	ds_read_b64_tr_b16 v[112:113], v175 offset:9728
	ds_read_b64_tr_b16 v[114:115], v176 offset:9728
	v_exp_f32_e32 v90, v98
	v_exp_f32_e32 v89, v99
	s_waitcnt lgkmcnt(2)
	v_mfma_f32_32x32x16_bf16 v[16:31], v[68:71], v[64:67], v[16:31]
	ds_read_b64_tr_b16 v[96:97], v175 offset:12288
	ds_read_b64_tr_b16 v[98:99], v176 offset:12288
	v_exp_f32_e32 v72, v100
	v_exp_f32_e32 v73, v101
	s_waitcnt lgkmcnt(2)
	v_mfma_f32_32x32x16_bf16 v[0:15], v[112:115], v[64:67], v[0:15]
	ds_read_b64_tr_b16 v[116:117], v175 offset:12800
	ds_read_b64_tr_b16 v[118:119], v176 offset:12800
	v_exp_f32_e32 v78, v102
	v_exp_f32_e32 v77, v103
	s_waitcnt lgkmcnt(2)
	v_mfma_f32_32x32x16_bf16 v[48:63], v[96:99], v[160:163], v[48:63]
	ds_read_b64_tr_b16 v[64:65], v175 offset:13312
	ds_read_b64_tr_b16 v[66:67], v176 offset:13312
	v_exp_f32_e32 v68, v104
	v_exp_f32_e32 v69, v105
	s_waitcnt lgkmcnt(2)
	v_mfma_f32_32x32x16_bf16 v[32:47], v[116:119], v[160:163], v[32:47]
	ds_read_b64_tr_b16 v[96:97], v175 offset:13824
	ds_read_b64_tr_b16 v[98:99], v176 offset:13824
	v_exp_f32_e32 v70, v106
	v_exp_f32_e32 v71, v107
	s_waitcnt lgkmcnt(2)
	v_mfma_f32_32x32x16_bf16 v[16:31], v[64:67], v[160:163], v[16:31]
	v_exp_f32_e32 v64, v108
	v_exp_f32_e32 v65, v109
	s_waitcnt lgkmcnt(0)
	v_mfma_f32_32x32x16_bf16 v[0:15], v[96:99], v[160:163], v[0:15]
	v_exp_f32_e32 v66, v110
	v_exp_f32_e32 v67, v111
	s_add_i32 s22, s23, 1
	s_cmp_lg_u32 s23, 2
	s_mov_b32 s20, s16
	s_mov_b32 s16, s19
	s_cselect_b32 s19, s22, 0
	s_add_i32 s18, s18, 2
	s_add_u32 s14, s14, 0x8000
	s_addc_u32 s15, s15, 0
	s_waitcnt vmcnt(4) lgkmcnt(0)
	s_barrier
	s_add_u32 s0, s0, 0x4000
	s_addc_u32 s1, s1, 0
	s_mov_b32 s21, s23
	s_cmpk_gt_u32 s18, 0x7c
	s_cbranch_scc0 .LBB0_340
	s_movk_i32 s53, 0x7f
	s_branch .LBB0_343

; #define AT_WAIT_BAR(N) asm volatile("s_waitcnt vmcnt(" #N ") lgkmcnt(0)\n\ts_barrier" ::: "memory")
; #define AT_ROT() do { sl_prev = sl_cur; sl_cur = sl_next; sl_next = (sl_next == 2) ? 0 : sl_next + 1; } while (0)
; #define AT_ENDW(tt) do { if ((tt) + 3 < NT) { AT_WAIT_BAR(4); } else if ((tt) + 2 < NT) { AT_WAIT_BAR(2); } else { AT_WAIT_BAR(0); } } while (0)
; __device__ __forceinline__ void attn_unit(LAS unsigned char* lds, const bf16_t* Qb, const bf16_t* Kb, const bf16_t* Vb, bf16_t* mix,
;                                           int b, int head, int qbase  , float lam, float post_scale, const float* subg) {
;     ...
;     int t = 1;
;     for (; t + 5 < NT; t += 2) {
;         AT_STEP(pB0, pB1, pA0, pA1, t, true, true, true);     AT_WAIT_BAR(4); AT_ROT();
;         AT_STEP(pA0, pA1, pB0, pB1, t + 1, true, true, true); AT_WAIT_BAR(4); AT_ROT();
;     }
;     for (; t + 1 < NT; t += 2) {
;         AT_STEP(pB0, pB1, pA0, pA1, t, (t + 3 < NT), (t + 1 < NT), (t + 1 < NT));         AT_ENDW(t);     AT_ROT();
;         AT_STEP(pA0, pA1, pB0, pB1, t + 1, (t + 4 < NT), (t + 2 < NT), (t + 2 < NT));     AT_ENDW(t + 1); AT_ROT();
.LBB0_345:
	s_and_b32 s31, s23, 0xc000
	v_add_u32_e32 v96, s31, v173
	ds_read_b128 v[182:185], v96 offset:4096
	ds_read_b128 v[186:189], v96 offset:4608
	ds_read_b128 v[190:193], v96 offset:6144
	ds_read_b128 v[194:197], v96 offset:6656
	s_lshl_b32 s0, s0, 14
	s_add_i32 s0, s0, 0
	v_add_f32_e32 v96, v177, v80
	v_cvt_pk_bf16_f32 v164, v80, v79
	v_cvt_pk_bf16_f32 v165, v88, v87
	v_add_f32_e32 v96, v96, v79
	v_add_f32_e32 v96, v96, v88
	v_add_f32_e32 v112, v96, v87
	s_waitcnt lgkmcnt(7)
	v_mfma_f32_32x32x16_bf16 v[96:111], v[156:159], v[140:143], 0
	v_add_f32_e32 v79, v112, v82
	s_waitcnt lgkmcnt(6)
	v_mfma_f32_32x32x16_bf16 v[112:127], v[148:151], v[140:143], 0
	v_add_f32_e32 v79, v79, v83
	v_cvt_pk_bf16_f32 v166, v82, v83
	v_cvt_pk_bf16_f32 v167, v92, v91
	v_add_f32_e32 v79, v79, v92
	v_add_f32_e32 v79, v79, v91
	s_waitcnt lgkmcnt(5)
	v_mfma_f32_32x32x16_bf16 v[96:111], v[152:155], v[136:139], v[96:111]
	v_add_f32_e32 v79, v79, v76
	v_cvt_pk_bf16_f32 v160, v76, v75
	v_cvt_pk_bf16_f32 v161, v86, v85
	v_add_f32_e32 v79, v79, v75
	v_add_f32_e32 v79, v79, v86
	v_add_f32_e32 v79, v79, v85
	s_waitcnt lgkmcnt(4)
	v_mfma_f32_32x32x16_bf16 v[112:127], v[144:147], v[136:139], v[112:127]
	v_add_f32_e32 v75, v79, v74
	v_cvt_pk_bf16_f32 v162, v74, v93
	v_cvt_pk_bf16_f32 v163, v94, v95
	v_add_f32_e32 v75, v75, v93
	v_add_f32_e32 v75, v75, v94
	v_add_f32_e32 v75, v75, v95
	s_waitcnt lgkmcnt(3)
	v_mfma_f32_32x32x16_bf16 v[96:111], v[182:185], v[132:135], v[96:111]
	v_add_f32_e32 v74, v75, v84
	v_add_f32_e32 v74, v74, v81
	v_add_f32_e32 v74, v74, v90
	v_add_f32_e32 v76, v74, v89
	v_cvt_pk_bf16_f32 v74, v84, v81
	v_cvt_pk_bf16_f32 v75, v90, v89
	s_waitcnt lgkmcnt(2)
	v_mfma_f32_32x32x16_bf16 v[112:127], v[186:189], v[132:135], v[112:127]
	v_add_f32_e32 v76, v76, v72
	v_add_f32_e32 v76, v76, v73
	v_add_f32_e32 v76, v76, v78
	v_add_f32_e32 v86, v76, v77
	v_cvt_pk_bf16_f32 v76, v72, v73
	v_cvt_pk_bf16_f32 v77, v78, v77
	v_add_u32_e32 v72, s0, v170
	v_add_u32_e32 v73, s0, v171
	ds_read_b64_tr_b16 v[82:83], v72
	ds_read_b64_tr_b16 v[84:85], v73
	ds_read_b64_tr_b16 v[80:81], v73 offset:512
	ds_read_b64_tr_b16 v[78:79], v72 offset:512
	s_waitcnt lgkmcnt(5)
	v_mfma_f32_32x32x16_bf16 v[96:111], v[190:193], v[128:131], v[96:111]
	v_add_f32_e32 v86, v86, v68
	v_cvt_pk_bf16_f32 v68, v68, v69
	v_add_f32_e32 v86, v86, v69
	v_cvt_pk_bf16_f32 v69, v70, v71
	v_add_f32_e32 v86, v86, v70
	v_add_f32_e32 v86, v86, v71
	s_waitcnt lgkmcnt(4)
	v_mfma_f32_32x32x16_bf16 v[112:127], v[194:197], v[128:131], v[112:127]
	v_add_f32_e32 v70, v86, v64
	v_add_f32_e32 v70, v70, v65
	v_add_f32_e32 v70, v70, v66
	v_add_f32_e32 v89, v70, v67
	v_cvt_pk_bf16_f32 v70, v64, v65
	v_cvt_pk_bf16_f32 v71, v66, v67
	s_add_i32 s0, s52, 1
	s_cmp_ge_u32 s0, s20
	s_cselect_b64 s[14:15], -1, 0
	s_and_b64 vcc, exec, s[14:15]
	s_cbranch_vccnz .LBB0_347
	s_add_i32 s0, s23, 0xc000
	s_and_b32 s0, s0, 0xc000
	s_add_i32 s0, s0, s46
	s_add_i32 s16, s0, 0
	s_add_u32 s17, s27, s49
	s_addc_u32 s18, s28, 0
	s_add_u32 s0, s17, 0x9d06000
	s_addc_u32 s1, s18, 0
	s_mov_b32 s19, m0
	s_mov_b32 m0, s16
	s_nop 0
	global_load_lds_dwordx4 v172, s[0:1]
	s_mov_b32 m0, s19
	s_add_u32 s0, s17, 0x9e0e000
	s_addc_u32 s1, s18, 0
	s_addk_i32 s16, 0x2000
	s_mov_b32 s17, m0
	s_mov_b32 m0, s16
	s_nop 0
	global_load_lds_dwordx4 v172, s[0:1]
	s_mov_b32 m0, s17

; #define AT_WAIT_BAR(N) asm volatile("s_waitcnt vmcnt(" #N ") lgkmcnt(0)\n\ts_barrier" ::: "memory")
; #define AT_ROT() do { sl_prev = sl_cur; sl_cur = sl_next; sl_next = (sl_next == 2) ? 0 : sl_next + 1; } while (0)
; #define AT_ENDW(tt) do { if ((tt) + 3 < NT) { AT_WAIT_BAR(4); } else if ((tt) + 2 < NT) { AT_WAIT_BAR(2); } else { AT_WAIT_BAR(0); } } while (0)
; __device__ __forceinline__ void attn_unit(LAS unsigned char* lds, const bf16_t* Qb, const bf16_t* Kb, const bf16_t* Vb, bf16_t* mix,
;                                           int b, int head, int qbase  , float lam, float post_scale, const float* subg) {
;     ...
;     int t = 1;
;     for (; t + 5 < NT; t += 2) {
;         AT_STEP(pB0, pB1, pA0, pA1, t, true, true, true);     AT_WAIT_BAR(4); AT_ROT();
;         AT_STEP(pA0, pA1, pB0, pB1, t + 1, true, true, true); AT_WAIT_BAR(4); AT_ROT();
;     }
;     for (; t + 1 < NT; t += 2) {
;         AT_STEP(pB0, pB1, pA0, pA1, t, (t + 3 < NT), (t + 1 < NT), (t + 1 < NT));         AT_ENDW(t);     AT_ROT();
;         AT_STEP(pA0, pA1, pB0, pB1, t + 1, (t + 4 < NT), (t + 2 < NT), (t + 2 < NT));     AT_ENDW(t + 1); AT_ROT();
.LBB0_355:
	v_exp_f32_e32 v65, v96
	v_exp_f32_e32 v66, v97
	v_exp_f32_e32 v67, v98
	v_exp_f32_e32 v68, v99
	v_exp_f32_e32 v69, v100
	v_exp_f32_e32 v70, v101
	v_exp_f32_e32 v71, v102
	v_exp_f32_e32 v79, v103
	v_exp_f32_e32 v84, v104
	v_exp_f32_e32 v85, v105
	v_exp_f32_e32 v86, v106
	v_exp_f32_e32 v87, v107
	v_exp_f32_e32 v88, v108
	v_exp_f32_e32 v90, v109
	v_exp_f32_e32 v91, v110
	v_exp_f32_e32 v164, v111
	v_exp_f32_e32 v165, v112
	v_exp_f32_e32 v166, v113
	v_exp_f32_e32 v167, v114
	v_exp_f32_e32 v175, v115
	v_exp_f32_e32 v176, v116
	v_exp_f32_e32 v182, v117
	v_exp_f32_e32 v183, v118
	v_exp_f32_e32 v184, v119
	v_exp_f32_e32 v185, v120
	v_exp_f32_e32 v186, v121
	v_exp_f32_e32 v187, v122
	v_exp_f32_e32 v188, v123
	v_exp_f32_e32 v189, v124
	v_exp_f32_e32 v190, v125
	v_exp_f32_e32 v191, v126
	v_exp_f32_e32 v192, v127
	ds_read_b128 v[72:75], v64 offset:4096
	ds_read_b128 v[80:83], v64 offset:4608
	ds_read_b128 v[92:95], v64 offset:6144
	ds_read_b128 v[160:163], v64 offset:6656
	s_lshl_b32 s0, s29, 14
	s_add_i32 s0, s0, 0
	v_mfma_f32_32x32x16_bf16 v[112:127], v[156:159], v[140:143], 0
	v_add_f32_e32 v64, v177, v65
	v_cvt_pk_bf16_f32 v76, v65, v66
	v_cvt_pk_bf16_f32 v77, v67, v68
	v_add_f32_e32 v64, v64, v66
	v_add_f32_e32 v64, v64, v67
	v_add_f32_e32 v64, v64, v68
	v_mfma_f32_32x32x16_bf16 v[96:111], v[148:151], v[140:143], 0
	v_add_f32_e32 v64, v64, v69
	v_cvt_pk_bf16_f32 v78, v69, v70
	v_add_f32_e32 v64, v64, v70
	v_add_f32_e32 v64, v64, v71
	v_add_f32_e32 v64, v64, v79
	v_cvt_pk_bf16_f32 v79, v71, v79
	v_mfma_f32_32x32x16_bf16 v[112:127], v[152:155], v[136:139], v[112:127]
	v_add_f32_e32 v64, v64, v84
	v_cvt_pk_bf16_f32 v68, v84, v85
	v_cvt_pk_bf16_f32 v69, v86, v87
	v_add_f32_e32 v64, v64, v85
	v_add_f32_e32 v64, v64, v86
	v_add_f32_e32 v64, v64, v87
	v_mfma_f32_32x32x16_bf16 v[96:111], v[144:147], v[136:139], v[96:111]
	v_add_f32_e32 v64, v64, v88
	v_cvt_pk_bf16_f32 v70, v88, v90
	v_cvt_pk_bf16_f32 v71, v91, v164
	v_add_f32_e32 v64, v64, v90
	v_add_f32_e32 v64, v64, v91
	v_add_f32_e32 v64, v64, v164
	s_waitcnt lgkmcnt(3)
	v_mfma_f32_32x32x16_bf16 v[112:127], v[72:75], v[132:135], v[112:127]
	v_add_f32_e32 v64, v64, v165
	v_add_f32_e32 v64, v64, v166
	v_add_f32_e32 v64, v64, v167
	v_add_f32_e32 v66, v64, v175
	v_cvt_pk_bf16_f32 v64, v165, v166
	v_cvt_pk_bf16_f32 v65, v167, v175
	s_waitcnt lgkmcnt(2)
	v_mfma_f32_32x32x16_bf16 v[96:111], v[80:83], v[132:135], v[96:111]
	v_add_f32_e32 v66, v66, v176
	v_add_f32_e32 v66, v66, v182
	v_add_f32_e32 v66, v66, v183
	v_add_f32_e32 v72, v66, v184
	v_cvt_pk_bf16_f32 v66, v176, v182
	v_cvt_pk_bf16_f32 v67, v183, v184
	v_add_u32_e32 v88, s0, v170
	v_add_u32_e32 v91, s0, v171
	ds_read_b64_tr_b16 v[84:85], v88
	ds_read_b64_tr_b16 v[86:87], v91
	ds_read_b64_tr_b16 v[82:83], v91 offset:512
	ds_read_b64_tr_b16 v[80:81], v88 offset:512
	s_waitcnt lgkmcnt(5)
	v_mfma_f32_32x32x16_bf16 v[112:127], v[92:95], v[128:131], v[112:127]
	v_add_f32_e32 v72, v72, v185
	v_add_f32_e32 v72, v72, v186
	v_add_f32_e32 v72, v72, v187
	v_add_f32_e32 v74, v72, v188
	v_cvt_pk_bf16_f32 v72, v185, v186
	v_cvt_pk_bf16_f32 v73, v187, v188
	s_waitcnt lgkmcnt(4)
	v_mfma_f32_32x32x16_bf16 v[96:111], v[160:163], v[128:131], v[96:111]
	v_add_f32_e32 v74, v74, v189
	v_add_f32_e32 v74, v74, v190
	v_add_f32_e32 v74, v74, v191
	v_add_f32_e32 v90, v74, v192
	v_cvt_pk_bf16_f32 v74, v189, v190
	v_cvt_pk_bf16_f32 v75, v191, v192
	s_add_i32 s55, s52, 2
	s_cmp_ge_u32 s55, s20
	s_cselect_b64 s[16:17], -1, 0
	s_and_b64 vcc, exec, s[16:17]
	s_cbranch_vccnz .LBB0_357
	s_add_i32 s0, s31, s46
	s_add_i32 s18, s0, 0
	s_add_u32 s19, s27, s49
	s_addc_u32 s29, s28, 0
	s_add_u32 s0, s19, 0x9d08000
	s_addc_u32 s1, s29, 0
	s_mov_b32 s56, m0
	s_mov_b32 m0, s18
	s_nop 0
	global_load_lds_dwordx4 v172, s[0:1]
	s_mov_b32 m0, s56
	s_add_u32 s0, s19, 0x9e10000
	s_addc_u32 s1, s29, 0
	s_addk_i32 s18, 0x2000
	s_mov_b32 s19, m0
	s_mov_b32 m0, s18
	s_nop 0
	global_load_lds_dwordx4 v172, s[0:1]
	s_mov_b32 m0, s19

; #define AT_WAIT_BAR(N) asm volatile("s_waitcnt vmcnt(" #N ") lgkmcnt(0)\n\ts_barrier" ::: "memory")
; #define AT_ROT() do { sl_prev = sl_cur; sl_cur = sl_next; sl_next = (sl_next == 2) ? 0 : sl_next + 1; } while (0)
; #define AT_ENDW(tt) do { if ((tt) + 3 < NT) { AT_WAIT_BAR(4); } else if ((tt) + 2 < NT) { AT_WAIT_BAR(2); } else { AT_WAIT_BAR(0); } } while (0)
; __device__ __forceinline__ void attn_unit(LAS unsigned char* lds, const bf16_t* Qb, const bf16_t* Kb, const bf16_t* Vb, bf16_t* mix,
;                                           int b, int head, int qbase  , float lam, float post_scale, const float* subg) {
;     ...
;     int t = 1;
;     for (; t + 5 < NT; t += 2) {
;         AT_STEP(pB0, pB1, pA0, pA1, t, true, true, true);     AT_WAIT_BAR(4); AT_ROT();
;         AT_STEP(pA0, pA1, pB0, pB1, t + 1, true, true, true); AT_WAIT_BAR(4); AT_ROT();
;     }
;     for (; t + 1 < NT; t += 2) {
;         AT_STEP(pB0, pB1, pA0, pA1, t, (t + 3 < NT), (t + 1 < NT), (t + 1 < NT));         AT_ENDW(t);     AT_ROT();
;         AT_STEP(pA0, pA1, pB0, pB1, t + 1, (t + 4 < NT), (t + 2 < NT), (t + 2 < NT));     AT_ENDW(t + 1); AT_ROT();
;     }
;     AT_STEP(pB0, pB1, pA0, pA1, NT - 1, false, false, false);
.LBB0_375:
	ds_read_b128 v[164:167], v173 offset:53248
	ds_read_b128 v[182:185], v173 offset:53760
	ds_read_b128 v[186:189], v173 offset:55296
	ds_read_b128 v[190:193], v173 offset:55808
	s_add_i32 s1, s30, 0
	v_add_f32_e32 v96, v177, v80
	v_cvt_pk_bf16_f32 v160, v80, v79
	v_cvt_pk_bf16_f32 v161, v88, v87
	s_waitcnt lgkmcnt(7)
	v_mfma_f32_32x32x16_bf16 v[112:127], v[156:159], v[140:143], 0
	v_add_f32_e32 v96, v96, v79
	v_add_f32_e32 v96, v96, v88
	v_add_f32_e32 v96, v96, v87
	v_add_f32_e32 v79, v96, v82
	v_cvt_pk_bf16_f32 v162, v82, v83
	v_cvt_pk_bf16_f32 v163, v92, v91
	s_waitcnt lgkmcnt(6)
	v_mfma_f32_32x32x16_bf16 v[96:111], v[148:151], v[140:143], 0
	v_add_f32_e32 v79, v79, v83
	v_add_f32_e32 v79, v79, v92
	v_add_f32_e32 v79, v79, v91
	v_add_f32_e32 v79, v79, v76
	s_waitcnt lgkmcnt(5)
	v_mfma_f32_32x32x16_bf16 v[112:127], v[152:155], v[136:139], v[112:127]
	v_add_f32_e32 v79, v79, v75
	v_cvt_pk_bf16_f32 v140, v76, v75
	v_cvt_pk_bf16_f32 v141, v86, v85
	v_add_f32_e32 v79, v79, v86
	v_add_f32_e32 v79, v79, v85
	v_add_f32_e32 v75, v79, v74
	s_waitcnt lgkmcnt(4)
	v_mfma_f32_32x32x16_bf16 v[96:111], v[144:147], v[136:139], v[96:111]
	v_add_f32_e32 v75, v75, v93
	v_cvt_pk_bf16_f32 v142, v74, v93
	v_cvt_pk_bf16_f32 v143, v94, v95
	v_add_f32_e32 v75, v75, v94
	v_add_f32_e32 v75, v75, v95
	v_add_f32_e32 v74, v75, v84
	s_waitcnt lgkmcnt(3)
	v_mfma_f32_32x32x16_bf16 v[112:127], v[164:167], v[132:135], v[112:127]
	v_add_f32_e32 v74, v74, v81
	v_add_f32_e32 v74, v74, v90
	v_add_f32_e32 v76, v74, v89
	v_cvt_pk_bf16_f32 v74, v84, v81
	v_cvt_pk_bf16_f32 v75, v90, v89
	v_add_f32_e32 v76, v76, v72
	s_waitcnt lgkmcnt(2)
	v_mfma_f32_32x32x16_bf16 v[96:111], v[182:185], v[132:135], v[96:111]
	v_add_f32_e32 v76, v76, v73
	v_add_f32_e32 v76, v76, v78
	v_add_f32_e32 v86, v76, v77
	v_cvt_pk_bf16_f32 v76, v72, v73
	v_cvt_pk_bf16_f32 v77, v78, v77
	v_add_u32_e32 v72, s1, v170
	v_add_u32_e32 v87, s1, v171
	ds_read_b64_tr_b16 v[78:79], v72
	ds_read_b64_tr_b16 v[80:81], v87
	ds_read_b64_tr_b16 v[84:85], v87 offset:512
	ds_read_b64_tr_b16 v[82:83], v72 offset:512
	v_add_f32_e32 v73, v86, v68
	s_waitcnt lgkmcnt(5)
	v_mfma_f32_32x32x16_bf16 v[112:127], v[186:189], v[128:131], v[112:127]
	v_add_f32_e32 v73, v73, v69
	v_cvt_pk_bf16_f32 v68, v68, v69
	v_cvt_pk_bf16_f32 v69, v70, v71
	v_add_f32_e32 v73, v73, v70
	v_add_f32_e32 v73, v73, v71
	v_add_f32_e32 v70, v73, v64
	s_waitcnt lgkmcnt(4)
	v_mfma_f32_32x32x16_bf16 v[96:111], v[190:193], v[128:131], v[96:111]
	v_add_f32_e32 v70, v70, v65
	v_add_f32_e32 v70, v70, v66
	v_add_f32_e32 v86, v70, v67
	v_cvt_pk_bf16_f32 v70, v64, v65
	v_cvt_pk_bf16_f32 v71, v66, v67
	s_waitcnt lgkmcnt(2)
	v_mfma_f32_32x32x16_bf16 v[48:63], v[78:81], v[160:163], v[48:63]
	ds_read_b64_tr_b16 v[64:65], v72 offset:1024
	ds_read_b64_tr_b16 v[66:67], v87 offset:1024
	s_nop 0
	v_exp_f32_e32 v88, v112
	v_exp_f32_e32 v89, v113
	s_waitcnt lgkmcnt(2)
	v_mfma_f32_32x32x16_bf16 v[32:47], v[82:85], v[160:163], v[32:47]
	ds_read_b64_tr_b16 v[78:79], v72 offset:1536
	ds_read_b64_tr_b16 v[80:81], v87 offset:1536
	v_exp_f32_e32 v90, v114
	v_exp_f32_e32 v91, v115
	s_waitcnt lgkmcnt(2)
	v_mfma_f32_32x32x16_bf16 v[16:31], v[64:67], v[160:163], v[16:31]
	ds_read_b64_tr_b16 v[82:83], v72 offset:4096
	ds_read_b64_tr_b16 v[84:85], v87 offset:4096
	v_exp_f32_e32 v92, v116
	v_exp_f32_e32 v93, v117
	s_waitcnt lgkmcnt(2)
	v_mfma_f32_32x32x16_bf16 v[0:15], v[78:81], v[160:163], v[0:15]
	ds_read_b64_tr_b16 v[64:65], v72 offset:4608
	ds_read_b64_tr_b16 v[66:67], v87 offset:4608
	v_exp_f32_e32 v94, v118
	v_exp_f32_e32 v95, v119
	s_waitcnt lgkmcnt(2)
	v_mfma_f32_32x32x16_bf16 v[48:63], v[82:85], v[140:143], v[48:63]
	ds_read_b64_tr_b16 v[78:79], v72 offset:5120
	ds_read_b64_tr_b16 v[80:81], v87 offset:5120
	v_exp_f32_e32 v112, v120
	v_exp_f32_e32 v113, v121
	s_waitcnt lgkmcnt(2)
	v_mfma_f32_32x32x16_bf16 v[32:47], v[64:67], v[140:143], v[32:47]
	ds_read_b64_tr_b16 v[82:83], v72 offset:5632
	ds_read_b64_tr_b16 v[84:85], v87 offset:5632
	v_exp_f32_e32 v114, v122
	v_exp_f32_e32 v115, v123
	s_waitcnt lgkmcnt(2)
	v_mfma_f32_32x32x16_bf16 v[16:31], v[78:81], v[140:143], v[16:31]
	ds_read_b64_tr_b16 v[64:65], v72 offset:8192
	ds_read_b64_tr_b16 v[66:67], v87 offset:8192
	v_exp_f32_e32 v116, v124
	v_exp_f32_e32 v117, v125
	s_waitcnt lgkmcnt(2)
	v_mfma_f32_32x32x16_bf16 v[0:15], v[82:85], v[140:143], v[0:15]
	ds_read_b64_tr_b16 v[78:79], v72 offset:8704
	ds_read_b64_tr_b16 v[80:81], v87 offset:8704
	v_exp_f32_e32 v118, v126
	v_exp_f32_e32 v119, v127
	s_waitcnt lgkmcnt(2)
	v_mfma_f32_32x32x16_bf16 v[48:63], v[64:67], v[74:77], v[48:63]
	ds_read_b64_tr_b16 v[82:83], v72 offset:9216
	ds_read_b64_tr_b16 v[84:85], v87 offset:9216
	v_exp_f32_e32 v96, v96
	v_exp_f32_e32 v97, v97
	s_waitcnt lgkmcnt(2)
	v_mfma_f32_32x32x16_bf16 v[32:47], v[78:81], v[74:77], v[32:47]
	ds_read_b64_tr_b16 v[64:65], v72 offset:9728
	ds_read_b64_tr_b16 v[66:67], v87 offset:9728
	v_exp_f32_e32 v98, v98
	v_exp_f32_e32 v99, v99
	s_waitcnt lgkmcnt(2)
	v_mfma_f32_32x32x16_bf16 v[16:31], v[82:85], v[74:77], v[16:31]
	ds_read_b64_tr_b16 v[78:79], v72 offset:12288
	ds_read_b64_tr_b16 v[80:81], v87 offset:12288
	v_exp_f32_e32 v100, v100
	v_exp_f32_e32 v101, v101
	s_waitcnt lgkmcnt(2)
	v_mfma_f32_32x32x16_bf16 v[0:15], v[64:67], v[74:77], v[0:15]
	ds_read_b64_tr_b16 v[82:83], v72 offset:12800
	ds_read_b64_tr_b16 v[84:85], v87 offset:12800
	v_exp_f32_e32 v102, v102
	v_exp_f32_e32 v103, v103
	s_waitcnt lgkmcnt(2)
	v_mfma_f32_32x32x16_bf16 v[48:63], v[78:81], v[68:71], v[48:63]
	ds_read_b64_tr_b16 v[64:65], v72 offset:13312
	ds_read_b64_tr_b16 v[66:67], v87 offset:13312
	v_exp_f32_e32 v80, v104
	v_exp_f32_e32 v81, v105
	s_waitcnt lgkmcnt(2)
; #define LAS __attribute__((address_space(3)))
; #define LAS __attribute__((address_space(3)))
; #define AT_VFRAG(dst, vp, n) do { const s16x4 lo_ = tr16((vp) + vlo + ((n) >> 2) * 4096 + ((n) & 3) * 512), hi_ = tr16((vp) + vhi + ((n) >> 2) * 4096 + ((n) & 3) * 512); \
;         dst = (bf16x8){lo_[0], lo_[1], lo_[2], lo_[3], hi_[0], hi_[1], hi_[2], hi_[3]}; } while (0)
; #define AT_PK(P, B) pkbf(P[B], P[B + 1])
; __device__ __forceinline__ void attn_unit(LAS unsigned char* lds, const bf16_t* Qb, const bf16_t* Kb, const bf16_t* Vb, bf16_t* mix,
;                                           int b, int head, int qbase  , float lam, float post_scale, const float* subg) {
;     ...
;     AT_STEP(pB0, pB1, pA0, pA1, NT - 1, false, false, false);
;     {
;         float sacc = 0.f;
; #pragma unroll
;         for (int i = 0; i < 16; ++i) sacc += pB0[i] + pB1[i];
;         lsum += sacc;
;         pw0 = (u32x4){AT_PK(pB0, 0), AT_PK(pB0, 2), AT_PK(pB0, 4), AT_PK(pB0, 6)}; pw1 = (u32x4){AT_PK(pB0, 8), AT_PK(pB0, 10), AT_PK(pB0, 12), AT_PK(pB0, 14)};
;         pw2 = (u32x4){AT_PK(pB1, 0), AT_PK(pB1, 2), AT_PK(pB1, 4), AT_PK(pB1, 6)}; pw3 = (u32x4){AT_PK(pB1, 8), AT_PK(pB1, 10), AT_PK(pB1, 12), AT_PK(pB1, 14)};
;         const u32x4 pwv[4] = {pw0, pw1, pw2, pw3};
;         const LAS unsigned char* vp_ = lds + sl_cur * 16384;
; #pragma unroll
;         for (int n = 0; n < 16; ++n) { bf16x8 vf_; AT_VFRAG(vf_, vp_, n); O[n & 3] = __builtin_amdgcn_mfma_f32_32x32x16_bf16(vf_, __builtin_bit_cast(bf16x8, pwv[n >> 2]), O[n & 3], 0, 0, 0); }
;     }
	v_mfma_f32_32x32x16_bf16 v[32:47], v[82:85], v[68:71], v[32:47]
	ds_read_b64_tr_b16 v[72:73], v72 offset:13824
	ds_read_b64_tr_b16 v[74:75], v87 offset:13824
	v_exp_f32_e32 v87, v106
	v_exp_f32_e32 v104, v107
	s_waitcnt lgkmcnt(2)
	v_mfma_f32_32x32x16_bf16 v[16:31], v[64:67], v[68:71], v[16:31]
	v_exp_f32_e32 v67, v109
	v_exp_f32_e32 v66, v108
	s_waitcnt lgkmcnt(0)
	v_mfma_f32_32x32x16_bf16 v[0:15], v[72:75], v[68:71], v[0:15]
	v_exp_f32_e32 v82, v110
	v_exp_f32_e32 v83, v111
	s_add_i32 s0, s0, 0
	v_add_f32_e32 v121, v114, v87
	v_cvt_pk_bf16_f32 v72, v88, v89
	v_cvt_pk_bf16_f32 v73, v90, v91
	v_cvt_pk_bf16_f32 v74, v92, v93
	v_cvt_pk_bf16_f32 v75, v94, v95
	v_cvt_pk_bf16_f32 v76, v112, v113
	v_cvt_pk_bf16_f32 v77, v114, v115
	v_cvt_pk_bf16_f32 v78, v116, v117
	v_cvt_pk_bf16_f32 v79, v118, v119
	v_cvt_pk_bf16_f32 v68, v96, v97
	v_cvt_pk_bf16_f32 v69, v98, v99
	v_cvt_pk_bf16_f32 v70, v100, v101
	v_cvt_pk_bf16_f32 v71, v102, v103
	v_cvt_pk_bf16_f32 v64, v80, v81
	v_cvt_pk_bf16_f32 v65, v87, v104
	v_add_u32_e32 v87, s0, v170
	v_add_f32_e32 v84, v88, v96
	v_add_f32_e32 v111, v112, v80
	v_add_f32_e32 v120, v113, v81
	v_add_f32_e32 v123, v116, v66
	v_add_f32_e32 v124, v117, v67
	v_add_f32_e32 v125, v118, v82
	v_add_f32_e32 v126, v119, v83
	v_cvt_pk_bf16_f32 v66, v66, v67
	v_cvt_pk_bf16_f32 v67, v82, v83
	v_add_u32_e32 v88, s0, v171
	ds_read_b64_tr_b16 v[80:81], v87
	ds_read_b64_tr_b16 v[82:83], v88
	s_waitcnt lgkmcnt(0)
	v_mfma_f32_32x32x16_bf16 v[48:63], v[80:83], v[72:75], v[48:63]
	ds_read_b64_tr_b16 v[80:81], v87 offset:512
	ds_read_b64_tr_b16 v[82:83], v88 offset:512
	v_add_f32_e32 v85, v89, v97
	v_add_f32_e32 v105, v90, v98
	v_add_f32_e32 v106, v91, v99
	v_add_f32_e32 v107, v92, v100
	v_add_f32_e32 v108, v93, v101
	v_add_f32_e32 v109, v94, v102
	s_waitcnt lgkmcnt(0)
	v_mfma_f32_32x32x16_bf16 v[32:47], v[80:83], v[72:75], v[32:47]
	ds_read_b64_tr_b16 v[80:81], v87 offset:1024
	ds_read_b64_tr_b16 v[82:83], v88 offset:1024
	v_add_f32_e32 v110, v95, v103
	v_add_f32_e32 v122, v115, v104
	v_add_f32_e32 v86, v174, v86
	s_lshl_b32 s0, s44, 14
	s_add_i32 s0, s0, 0
	s_cmp_lg_u32 s45, 1
	s_waitcnt lgkmcnt(0)
	v_mfma_f32_32x32x16_bf16 v[16:31], v[80:83], v[72:75], v[16:31]
	ds_read_b64_tr_b16 v[80:81], v87 offset:1536
	ds_read_b64_tr_b16 v[82:83], v88 offset:1536
	s_waitcnt lgkmcnt(0)
	v_mfma_f32_32x32x16_bf16 v[0:15], v[80:83], v[72:75], v[0:15]
	ds_read_b64_tr_b16 v[72:73], v87 offset:4096
	ds_read_b64_tr_b16 v[74:75], v88 offset:4096
	s_waitcnt lgkmcnt(0)
	v_mfma_f32_32x32x16_bf16 v[48:63], v[72:75], v[76:79], v[48:63]
	ds_read_b64_tr_b16 v[72:73], v87 offset:4608
	ds_read_b64_tr_b16 v[74:75], v88 offset:4608
	s_waitcnt lgkmcnt(0)
	v_mfma_f32_32x32x16_bf16 v[32:47], v[72:75], v[76:79], v[32:47]
	ds_read_b64_tr_b16 v[72:73], v87 offset:5120
	ds_read_b64_tr_b16 v[74:75], v88 offset:5120
	s_waitcnt lgkmcnt(0)
	v_mfma_f32_32x32x16_bf16 v[16:31], v[72:75], v[76:79], v[16:31]
	ds_read_b64_tr_b16 v[72:73], v87 offset:5632
	ds_read_b64_tr_b16 v[74:75], v88 offset:5632
	s_waitcnt lgkmcnt(0)
	v_mfma_f32_32x32x16_bf16 v[0:15], v[72:75], v[76:79], v[0:15]
	ds_read_b64_tr_b16 v[72:73], v87 offset:8192
	ds_read_b64_tr_b16 v[74:75], v88 offset:8192
	s_waitcnt lgkmcnt(0)
	v_mfma_f32_32x32x16_bf16 v[48:63], v[72:75], v[68:71], v[48:63]
	ds_read_b64_tr_b16 v[72:73], v87 offset:8704
	ds_read_b64_tr_b16 v[74:75], v88 offset:8704
	s_waitcnt lgkmcnt(0)
	v_mfma_f32_32x32x16_bf16 v[32:47], v[72:75], v[68:71], v[32:47]
	ds_read_b64_tr_b16 v[72:73], v87 offset:9216
	ds_read_b64_tr_b16 v[74:75], v88 offset:9216
	s_waitcnt lgkmcnt(0)
	v_mfma_f32_32x32x16_bf16 v[16:31], v[72:75], v[68:71], v[16:31]
	ds_read_b64_tr_b16 v[72:73], v87 offset:9728
	ds_read_b64_tr_b16 v[74:75], v88 offset:9728
	s_waitcnt lgkmcnt(0)
	v_mfma_f32_32x32x16_bf16 v[0:15], v[72:75], v[68:71], v[0:15]
	ds_read_b64_tr_b16 v[68:69], v87 offset:12288
	ds_read_b64_tr_b16 v[70:71], v88 offset:12288
	s_waitcnt lgkmcnt(0)
	v_mfma_f32_32x32x16_bf16 v[48:63], v[68:71], v[64:67], v[48:63]
	ds_read_b64_tr_b16 v[68:69], v87 offset:12800
	ds_read_b64_tr_b16 v[70:71], v88 offset:12800
	s_waitcnt lgkmcnt(0)
	v_mfma_f32_32x32x16_bf16 v[32:47], v[68:71], v[64:67], v[32:47]
	ds_read_b64_tr_b16 v[68:69], v87 offset:13312
	ds_read_b64_tr_b16 v[70:71], v88 offset:13312
	s_waitcnt lgkmcnt(0)
	v_mfma_f32_32x32x16_bf16 v[16:31], v[68:71], v[64:67], v[16:31]
	ds_read_b64_tr_b16 v[68:69], v87 offset:13824
	ds_read_b64_tr_b16 v[70:71], v88 offset:13824
	s_waitcnt vmcnt(0) lgkmcnt(0)
	s_barrier
; #define LAS __attribute__((address_space(3)))
; #define LAS __attribute__((address_space(3)))
; __device__ __forceinline__ void attn_unit(LAS unsigned char* lds, const bf16_t* Qb, const bf16_t* Kb, const bf16_t* Vb, bf16_t* mix,
;                                           int b, int head, int qbase  , float lam, float post_scale, const float* subg) {
;     ...
;     asm volatile("s_waitcnt vmcnt(0) lgkmcnt(0)" ::: "memory");
;     __builtin_amdgcn_s_barrier();
;     asm volatile("" ::: "memory");
;     const float lt = lsum + __shfl_xor(lsum, 32);
;     int tid_e = threadIdx.x; asm volatile("" : "+v"(tid_e));
;     const int lane_e = tid_e & 63, h_e = lane_e >> 5, qidx_e = qbase + qg * 32 + (lane_e & 31);
;     LAS float* X = (LAS float*)lds + qg * 4096 + lane_e;
;     if (c == 1) {
;         const float sc = lam / lt;
; #pragma unroll
;         for (int d = 0; d < 4; ++d)
; #pragma unroll
;             for (int i = 0; i < 16; ++i) X[(d * 16 + i) * 64] = O[d][i] * sc;
;     }
	s_waitcnt lgkmcnt(0)
	v_mfma_f32_32x32x16_bf16 v[0:15], v[68:71], v[64:67], v[0:15]
	v_add_f32_e32 v64, 0, v84
	v_add_f32_e32 v64, v85, v64
	v_add_f32_e32 v64, v105, v64
	v_add_f32_e32 v64, v106, v64
	v_add_f32_e32 v64, v107, v64
	v_add_f32_e32 v64, v108, v64
	v_add_f32_e32 v64, v109, v64
	v_add_f32_e32 v64, v110, v64
	v_add_f32_e32 v64, v111, v64
	v_add_f32_e32 v64, v120, v64
	v_add_f32_e32 v64, v121, v64
	v_add_f32_e32 v64, v122, v64
	v_add_f32_e32 v64, v123, v64
	v_and_b32_e32 v66, 64, v229
	v_add_f32_e32 v64, v124, v64
	v_xor_b32_e32 v65, 32, v229
	v_add_u32_e32 v66, 64, v66
	v_add_f32_e32 v64, v125, v64
	v_cmp_lt_i32_e32 vcc, v65, v66
	v_add_f32_e32 v64, v126, v64
	v_add_f32_e32 v64, v86, v64
	v_cndmask_b32_e32 v65, v229, v65, vcc
	v_lshlrev_b32_e32 v78, 2, v65
	ds_bpermute_b32 v65, v78, v64
	v_mov_b32_e32 v67, v222
	s_waitcnt lgkmcnt(0)
	v_add_f32_e32 v64, v64, v65
	v_and_b32_e32 v65, 63, v67
	v_lshl_add_u32 v79, v65, 2, s0
	s_cbranch_scc1 .LBB0_377
	v_div_scale_f32 v65, s[0:1], v64, v64, v168
	v_rcp_f32_e32 v66, v65
	v_div_scale_f32 v68, vcc, v168, v64, v168
	v_fma_f32 v69, -v65, v66, 1.0
	v_fmac_f32_e32 v66, v69, v66
	v_mul_f32_e32 v69, v68, v66
	v_fma_f32 v70, -v65, v69, v68
	v_fmac_f32_e32 v69, v70, v66
	v_fma_f32 v65, -v65, v69, v68
	v_div_fmas_f32 v65, v65, v66, v69
	v_div_fixup_f32 v65, v65, v64, v168
	v_mul_f32_e32 v66, v48, v65
	v_mul_f32_e32 v68, v49, v65
	ds_write2st64_b32 v79, v66, v68 offset1:1
	v_mul_f32_e32 v66, v50, v65
	v_mul_f32_e32 v68, v51, v65
	ds_write2st64_b32 v79, v66, v68 offset0:2 offset1:3
	v_mul_f32_e32 v66, v52, v65
	v_mul_f32_e32 v68, v53, v65
	ds_write2st64_b32 v79, v66, v68 offset0:4 offset1:5
	v_mul_f32_e32 v66, v54, v65
	v_mul_f32_e32 v68, v55, v65
	ds_write2st64_b32 v79, v66, v68 offset0:6 offset1:7
	v_mul_f32_e32 v66, v56, v65
	v_mul_f32_e32 v68, v57, v65
	ds_write2st64_b32 v79, v66, v68 offset0:8 offset1:9
	v_mul_f32_e32 v66, v58, v65
	v_mul_f32_e32 v68, v59, v65
	ds_write2st64_b32 v79, v66, v68 offset0:10 offset1:11
	v_mul_f32_e32 v66, v60, v65
	v_mul_f32_e32 v68, v61, v65
	ds_write2st64_b32 v79, v66, v68 offset0:12 offset1:13
	v_mul_f32_e32 v66, v62, v65
	v_mul_f32_e32 v68, v63, v65
	ds_write2st64_b32 v79, v66, v68 offset0:14 offset1:15
	v_mul_f32_e32 v66, v32, v65
	v_mul_f32_e32 v68, v33, v65
	ds_write2st64_b32 v79, v66, v68 offset0:16 offset1:17
	v_mul_f32_e32 v66, v34, v65
	v_mul_f32_e32 v68, v35, v65
	ds_write2st64_b32 v79, v66, v68 offset0:18 offset1:19
	v_mul_f32_e32 v66, v36, v65
	v_mul_f32_e32 v68, v37, v65
	ds_write2st64_b32 v79, v66, v68 offset0:20 offset1:21
	v_mul_f32_e32 v66, v38, v65
	v_mul_f32_e32 v68, v39, v65
	ds_write2st64_b32 v79, v66, v68 offset0:22 offset1:23
	v_mul_f32_e32 v66, v40, v65
	v_mul_f32_e32 v68, v41, v65
	ds_write2st64_b32 v79, v66, v68 offset0:24 offset1:25
	v_mul_f32_e32 v66, v42, v65
	v_mul_f32_e32 v68, v43, v65
	ds_write2st64_b32 v79, v66, v68 offset0:26 offset1:27
	v_mul_f32_e32 v66, v44, v65
	v_mul_f32_e32 v68, v45, v65
	ds_write2st64_b32 v79, v66, v68 offset0:28 offset1:29
	v_mul_f32_e32 v66, v46, v65
	v_mul_f32_e32 v68, v47, v65
	ds_write2st64_b32 v79, v66, v68 offset0:30 offset1:31
	v_mul_f32_e32 v66, v16, v65
	v_mul_f32_e32 v68, v17, v65
	ds_write2st64_b32 v79, v66, v68 offset0:32 offset1:33
	v_mul_f32_e32 v66, v18, v65
	v_mul_f32_e32 v68, v19, v65
	ds_write2st64_b32 v79, v66, v68 offset0:34 offset1:35
	v_mul_f32_e32 v66, v20, v65
	v_mul_f32_e32 v68, v21, v65
	ds_write2st64_b32 v79, v66, v68 offset0:36 offset1:37
	v_mul_f32_e32 v66, v22, v65
	v_mul_f32_e32 v68, v23, v65
	ds_write2st64_b32 v79, v66, v68 offset0:38 offset1:39
	v_mul_f32_e32 v66, v24, v65
	v_mul_f32_e32 v68, v25, v65
	ds_write2st64_b32 v79, v66, v68 offset0:40 offset1:41
	v_mul_f32_e32 v66, v26, v65
	v_mul_f32_e32 v68, v27, v65
	ds_write2st64_b32 v79, v66, v68 offset0:42 offset1:43
	v_mul_f32_e32 v66, v28, v65
	v_mul_f32_e32 v68, v29, v65
	ds_write2st64_b32 v79, v66, v68 offset0:44 offset1:45
	v_mul_f32_e32 v66, v30, v65
	v_mul_f32_e32 v68, v31, v65
	ds_write2st64_b32 v79, v66, v68 offset0:46 offset1:47
	v_mul_f32_e32 v66, v0, v65
	v_mul_f32_e32 v68, v1, v65
	ds_write2st64_b32 v79, v66, v68 offset0:48 offset1:49
	v_mul_f32_e32 v66, v2, v65
	v_mul_f32_e32 v68, v3, v65
	ds_write2st64_b32 v79, v66, v68 offset0:50 offset1:51
	v_mul_f32_e32 v66, v4, v65
	v_mul_f32_e32 v68, v5, v65
	ds_write2st64_b32 v79, v66, v68 offset0:52 offset1:53
	v_mul_f32_e32 v66, v6, v65
	v_mul_f32_e32 v68, v7, v65
	ds_write2st64_b32 v79, v66, v68 offset0:54 offset1:55
	v_mul_f32_e32 v66, v8, v65
	v_mul_f32_e32 v68, v9, v65
	ds_write2st64_b32 v79, v66, v68 offset0:56 offset1:57
	v_mul_f32_e32 v66, v10, v65
	v_mul_f32_e32 v68, v11, v65
	ds_write2st64_b32 v79, v66, v68 offset0:58 offset1:59
	v_mul_f32_e32 v66, v12, v65
	v_mul_f32_e32 v68, v13, v65
	ds_write2st64_b32 v79, v66, v68 offset0:60 offset1:61
	v_mul_f32_e32 v66, v14, v65
	v_mul_f32_e32 v65, v15, v65
	ds_write2st64_b32 v79, v66, v65 offset0:62 offset1:63

; #define AT_WAIT_BAR(N) asm volatile("s_waitcnt vmcnt(" #N ") lgkmcnt(0)\n\ts_barrier" ::: "memory")
; __device__ __forceinline__ void attn_unit(LAS unsigned char* lds, const bf16_t* Qb, const bf16_t* Kb, const bf16_t* Vb, bf16_t* mix,
;                                           int b, int head, int qbase  , float lam, float post_scale, const float* subg) {
;     int tid_l = threadIdx.x; asm volatile("" : "+v"(tid_l)); const int tid = tid_l, lane = tid & 63, wid = __builtin_amdgcn_readfirstlane(tid >> 6);
;     const int r = lane & 31, h = lane >> 5;
;     const int qg = wid & 3, c = wid >> 2;
;     const int NT = qbase < CTXL ? (CTXL / 64) : NTK;
;     const int qidx = qbase + qg * 32 + r;
;     const size_t bh = (size_t)(b * 4 + head);
;     const bf16_t* Qc = Qb + (bh * 2 + c) * (LK * 64);
;     const unsigned char* K0 = (const unsigned char*)(Kb + (bh * 2) * (LK * 64));
;     const unsigned char* V0 = (const unsigned char*)(Vb + bh * (LK * 128));
;     const unsigned goff = (unsigned)(wid * 1024 + lane * 16);
;     const unsigned ldsb = (unsigned)(size_t)lds;
;     constexpr int VRING = 65536;
;     ...
;     AT_DMA_K(0, 0); AT_DMA_V(0, 0); AT_DMA_K(1, 1);
;     bf16x8 q[4];
; #pragma unroll
;     for (int d0 = 0; d0 < 4; ++d0) q[d0] = *(const bf16x8*)(Qc + (size_t)(qidx >> 6) * 4096 + (size_t)(2 * d0 + h) * 512 + (size_t)(qidx & 63) * 8);
;     AT_DMA_K(2, 2);
;     f32x16 O[4];
; #pragma unroll
;     for (int d = 0; d < 4; ++d)
; #pragma unroll
;         for (int i = 0; i < 16; ++i) O[d][i] = 0.f;
;     float lsum = 0.f;
;     const int koff = c * 8192 + h * 1024 + r * 16;
;     const int g1 = (lane >> 4) & 1, qq = (lane & 15) >> 2, pp = lane & 3;
;     const int vlo = VRING + 64 * (4 * h + qq) + 16 * (2 * g1 + ((pp >> 1) ^ h)) + 8 * (pp & 1);
;     const int vhi = VRING + 2048 + 64 * (4 * h + qq) + 16 * (2 * (g1 ^ 1) + ((pp >> 1) ^ h)) + 8 * (pp & 1);
;     bf16x8 kf[8];
;     ...
;     f32x16 pA0, pA1, pB0, pB1;
;     u32x4 pw0, pw1, pw2, pw3;
;     const f32x16 zero16 = {0.f, 0.f, 0.f, 0.f, 0.f, 0.f, 0.f, 0.f, 0.f, 0.f, 0.f, 0.f, 0.f, 0.f, 0.f, 0.f};
;     int sl_prev = 0, sl_cur = 0, sl_next = 1;
;     ...
;     AT_WAIT_BAR(6);
;     AT_KLOAD2(0, 0); AT_KLOAD2(1, 0); AT_KLOAD2(2, 0); AT_KLOAD2(3, 0);
;     pA0 = __builtin_amdgcn_mfma_f32_32x32x16_bf16(kf[0], q[0], zero16, 0, 0, 0); pA1 = __builtin_amdgcn_mfma_f32_32x32x16_bf16(kf[1], q[0], zero16, 0, 0, 0);
; #pragma unroll
.LBB0_420:
	v_mov_b32_e32 v40, v222
	s_lshl_b32 s0, s42, 7
	v_readfirstlane_b32 s43, v40
	s_ashr_i32 s1, s43, 6
	s_and_b32 s45, s1, 3
	s_ashr_i32 s37, s42, 3
	s_and_b32 s0, s0, 0x80
	s_lshl_b32 s14, s45, 5
	s_bfe_u32 s36, s42, 0x20001
	v_and_b32_e32 v2, 31, v40
	s_or_b32 s38, s14, s0
	s_lshl_b32 s0, s37, 2
	v_or_b32_e32 v1, s14, v2
	s_or_b32 s14, s0, s36
	s_ashr_i32 s44, s43, 8
	s_ashr_i32 s15, s14, 31
	s_lshl_b64 s[26:27], s[14:15], 1
	s_ashr_i32 s0, s44, 31
	s_add_u32 s15, s26, s44
	s_addc_u32 s0, s27, s0
	s_mul_i32 s0, s0, 0x108000
	s_mul_hi_u32 s26, s15, 0x108000
	s_add_i32 s26, s26, s0
	s_mul_i32 s15, s15, 0x108000
	s_add_u32 s0, s31, s15
	s_addc_u32 s46, s34, s26
	s_mul_hi_i32 s15, s14, 0x210000
	s_mul_i32 s14, s14, 0x210000
	s_add_u32 s26, s35, s14
	s_addc_u32 s27, s39, s15
	s_add_u32 s14, s40, s14
	s_addc_u32 s15, s41, s15
	s_lshl_b32 s1, s1, 10
	v_and_b32_e32 v0, 63, v40
	s_add_i32 s53, s1, 0
	v_lshl_or_b32 v141, v0, 4, s1
	s_mov_b32 s49, m0
	s_mov_b32 m0, s53
	s_nop 0
	global_load_lds_dwordx4 v141, s[26:27]
	s_mov_b32 m0, s49
	s_add_u32 s54, s26, 0x108000
	s_addc_u32 s55, s27, 0
	s_add_i32 s49, s53, 0x2000
	s_mov_b32 s51, m0
	s_mov_b32 m0, s49
	s_nop 0
	global_load_lds_dwordx4 v141, s[54:55]
	s_mov_b32 m0, s51
	s_add_i32 s49, s53, 0x10000
	s_mov_b32 s51, m0
	s_mov_b32 m0, s49
	s_nop 0
	global_load_lds_dwordx4 v141, s[14:15]
	s_mov_b32 m0, s51
	s_add_u32 s54, s14, 0x2000
	s_addc_u32 s55, s15, 0
	s_add_i32 s51, s53, 0x12000
	s_mov_b32 s52, m0
	s_mov_b32 m0, s51
	s_nop 0
	global_load_lds_dwordx4 v141, s[54:55]
	s_mov_b32 m0, s52
	s_add_i32 s52, 0, 0x4000
	s_add_i32 s56, s1, s52
	s_add_u32 s54, s26, 0x2000
	s_addc_u32 s55, s27, 0
	s_mov_b32 s57, m0
	s_mov_b32 m0, s56
	s_nop 0
	global_load_lds_dwordx4 v141, s[54:55]
	s_mov_b32 m0, s57
	s_add_u32 s54, s26, 0x10a000
	s_addc_u32 s55, s27, 0
	s_add_i32 s56, s53, 0x6000
	s_mov_b32 s57, m0
	s_mov_b32 m0, s56
	s_nop 0
	global_load_lds_dwordx4 v141, s[54:55]
	s_mov_b32 m0, s57
	s_lshl_b32 s54, s38, 7
	s_and_b32 s54, s54, 0x6000
	s_add_u32 s54, s0, s54
	v_lshlrev_b32_e32 v0, 4, v1
	v_bfe_u32 v41, v40, 5, 1
	s_addc_u32 s55, s46, 0
	v_and_b32_e32 v176, 0x3f0, v0
	v_lshl_add_u64 v[0:1], s[54:55], 0, v[176:177]
	v_lshlrev_b32_e32 v176, 10, v41
	v_lshl_add_u64 v[0:1], v[0:1], 0, v[176:177]
	flat_load_dwordx4 v[108:111], v[0:1]
	flat_load_dwordx4 v[104:107], v[0:1] offset:2048
	v_add_co_u32_e32 v0, vcc, s96, v0
	s_add_i32 s46, 0, 0x8000
	s_nop 0
	v_addc_co_u32_e32 v1, vcc, 0, v1, vcc
	flat_load_dwordx4 v[100:103], v[0:1]
	flat_load_dwordx4 v[96:99], v[0:1] offset:2048
	s_add_i32 s1, s1, s46
	s_add_u32 s54, s26, 0x4000
	s_addc_u32 s55, s27, 0
	s_mov_b32 s0, m0
	s_mov_b32 m0, s1
	s_nop 0
	global_load_lds_dwordx4 v141, s[54:55]
	s_mov_b32 m0, s0
	s_add_u32 s54, s26, 0x10c000
	v_lshlrev_b32_e32 v0, 4, v2
	s_addc_u32 s55, s27, 0
	s_lshl_b32 s1, s44, 13
	s_add_i32 s0, s53, 0xa000
	s_mov_b32 s56, m0
	s_mov_b32 m0, s0
	s_nop 0
	global_load_lds_dwordx4 v141, s[54:55]
	s_mov_b32 m0, s56
	v_or3_b32 v0, s1, v176, v0
	s_waitcnt vmcnt(6) lgkmcnt(0)
	s_barrier
	v_add_u32_e32 v140, 0, v0
	ds_read_b128 v[0:3], v140
	ds_read_b128 v[16:19], v140 offset:512
	ds_read_b128 v[32:35], v140 offset:2048
	ds_read_b128 v[36:39], v140 offset:2560
	s_add_i32 s0, s53, 0xc000
	s_add_u32 s54, s26, 0x6000
	s_addc_u32 s55, s27, 0
	s_add_u32 s26, s26, 0x10e000
	s_addc_u32 s27, s27, 0
	v_lshrrev_b32_e32 v42, 1, v40
	v_lshlrev_b32_e32 v43, 1, v40
	v_lshlrev_b32_e32 v44, 8, v41
	s_waitcnt vmcnt(0) lgkmcnt(0)
	v_mfma_f32_32x32x16_bf16 v[0:15], v[0:3], v[108:111], 0
	v_mfma_f32_32x32x16_bf16 v[16:31], v[16:19], v[108:111], 0
	v_mfma_f32_32x32x16_bf16 v[0:15], v[32:35], v[104:107], v[0:15]
	v_mfma_f32_32x32x16_bf16 v[16:31], v[36:39], v[104:107], v[16:31]
	ds_read_b128 v[32:35], v140 offset:4096
	ds_read_b128 v[36:39], v140 offset:4608
	s_waitcnt lgkmcnt(1)
	v_mfma_f32_32x32x16_bf16 v[0:15], v[32:35], v[100:103], v[0:15]
	ds_read_b128 v[32:35], v140 offset:6144
	s_waitcnt lgkmcnt(1)
	v_mfma_f32_32x32x16_bf16 v[16:31], v[36:39], v[100:103], v[16:31]
	v_lshlrev_b32_e32 v36, 4, v40
	v_and_b32_e32 v45, 0xc0, v36
	ds_read_b128 v[36:39], v140 offset:6656
	s_waitcnt vmcnt(0) lgkmcnt(0)
	s_barrier
	s_mov_b32 s1, m0
	s_mov_b32 m0, s0
	s_nop 0
	global_load_lds_dwordx4 v141, s[54:55]
	s_mov_b32 m0, s1
	s_add_i32 s0, s53, 0xe000
	s_mov_b32 s1, m0
	s_mov_b32 m0, s0
	s_nop 0
	global_load_lds_dwordx4 v141, s[26:27]
	s_mov_b32 m0, s1
	s_waitcnt lgkmcnt(1)
	v_mfma_f32_32x32x16_bf16 v[0:15], v[32:35], v[96:99], v[0:15]
	s_add_i32 s0, s53, 0x14000
	v_lshlrev_b32_e32 v40, 3, v40
	s_add_u32 s26, s14, 0x4000
	v_bitop3_b32 v32, v42, v41, 1 bitop3:0x6c
	v_and_b32_e32 v33, 32, v43
	v_and_b32_e32 v34, 8, v40
	s_addc_u32 s27, s15, 0
	s_waitcnt lgkmcnt(0)
	v_mfma_f32_32x32x16_bf16 v[16:31], v[36:39], v[96:99], v[16:31]
	v_lshl_or_b32 v32, v32, 4, v33
	v_or3_b32 v33, v44, v45, v34
	s_mov_b32 s1, m0
	s_mov_b32 m0, s0
	s_nop 0
	global_load_lds_dwordx4 v141, s[26:27]
	s_mov_b32 m0, s1
	s_add_u32 s26, s14, 0x6000
	v_or_b32_e32 v34, v33, v32
	s_addc_u32 s27, s15, 0
	s_add_i32 s0, s53, 0x16000
	s_mov_b32 s1, m0
	s_mov_b32 m0, s0
	s_nop 0
	global_load_lds_dwordx4 v141, s[26:27]
	s_mov_b32 m0, s1
	v_or_b32_e32 v138, 0x10000, v34
	v_exp_f32_e32 v34, v0
	v_exp_f32_e32 v36, v1
	v_exp_f32_e32 v38, v2
	v_exp_f32_e32 v40, v3
	v_exp_f32_e32 v42, v4
	v_exp_f32_e32 v44, v5
	v_exp_f32_e32 v46, v6
	v_exp_f32_e32 v48, v7
	v_exp_f32_e32 v50, v8
	v_exp_f32_e32 v52, v9
	v_exp_f32_e32 v54, v10
	v_exp_f32_e32 v56, v11
	v_exp_f32_e32 v58, v12
	v_exp_f32_e32 v60, v13
	v_exp_f32_e32 v62, v14
	v_exp_f32_e32 v112, v15
	ds_read_b128 v[0:3], v140 offset:16384
	ds_read_b128 v[4:7], v140 offset:16896
	ds_read_b128 v[8:11], v140 offset:18432
	ds_read_b128 v[12:15], v140 offset:18944
	v_exp_f32_e32 v35, v16
	v_exp_f32_e32 v37, v17
	v_exp_f32_e32 v39, v18
	v_exp_f32_e32 v41, v19
	v_exp_f32_e32 v43, v20
	v_exp_f32_e32 v45, v21
	v_exp_f32_e32 v47, v22
	v_exp_f32_e32 v49, v23
	v_exp_f32_e32 v51, v24
	v_exp_f32_e32 v53, v25
	v_exp_f32_e32 v55, v26
	v_exp_f32_e32 v57, v27
	v_exp_f32_e32 v59, v28
	v_exp_f32_e32 v61, v29
	v_exp_f32_e32 v63, v30
	s_waitcnt vmcnt(4) lgkmcnt(0)
	s_barrier
; #define AT_WAIT_BAR(N) asm volatile("s_waitcnt vmcnt(" #N ") lgkmcnt(0)\n\ts_barrier" ::: "memory")
; #define AT_ROT() do { sl_prev = sl_cur; sl_cur = sl_next; sl_next = (sl_next == 2) ? 0 : sl_next + 1; } while (0)
; #define AT_ENDW(tt) do { if ((tt) + 3 < NT) { AT_WAIT_BAR(4); } else if ((tt) + 2 < NT) { AT_WAIT_BAR(2); } else { AT_WAIT_BAR(0); } } while (0)
; __device__ __forceinline__ void attn_unit(LAS unsigned char* lds, const bf16_t* Qb, const bf16_t* Kb, const bf16_t* Vb, bf16_t* mix,
;                                           int b, int head, int qbase  , float lam, float post_scale, const float* subg) {
;     ...
;     int t = 1;
;     for (; t + 5 < NT; t += 2) {
;         AT_STEP(pB0, pB1, pA0, pA1, t, true, true, true);     AT_WAIT_BAR(4); AT_ROT();
;         AT_STEP(pA0, pA1, pB0, pB1, t + 1, true, true, true); AT_WAIT_BAR(4); AT_ROT();
;     }
;     for (; t + 1 < NT; t += 2) {
;         AT_STEP(pB0, pB1, pA0, pA1, t, (t + 3 < NT), (t + 1 < NT), (t + 1 < NT));         AT_ENDW(t);     AT_ROT();
;         AT_STEP(pA0, pA1, pB0, pB1, t + 1, (t + 4 < NT), (t + 2 < NT), (t + 2 < NT));     AT_ENDW(t + 1); AT_ROT();
	v_exp_f32_e32 v115, v31
	v_bitop3_b32 v139, v33, s97, v32 bitop3:0x36
	ds_read_b128 v[16:19], v140 offset:20480
	ds_read_b128 v[20:23], v140 offset:20992
	ds_read_b128 v[24:27], v140 offset:22528
	ds_read_b128 v[28:31], v140 offset:23040
	s_waitcnt lgkmcnt(7)
	v_mfma_f32_32x32x16_bf16 v[80:95], v[0:3], v[108:111], 0
	v_add_f32_e32 v0, v177, v34
	v_add_f32_e32 v0, v0, v36
	v_add_f32_e32 v0, v0, v38
	v_add_f32_e32 v2, v0, v40
	v_cvt_pk_bf16_f32 v0, v34, v36
	v_cvt_pk_bf16_f32 v1, v38, v40
	s_waitcnt lgkmcnt(6)
	v_mfma_f32_32x32x16_bf16 v[64:79], v[4:7], v[108:111], 0
	v_add_f32_e32 v2, v2, v42
	v_add_f32_e32 v2, v2, v44
	v_add_f32_e32 v2, v2, v46
	v_add_f32_e32 v32, v2, v48
	v_cvt_pk_bf16_f32 v2, v42, v44
	v_cvt_pk_bf16_f32 v3, v46, v48
	s_waitcnt lgkmcnt(5)
	v_mfma_f32_32x32x16_bf16 v[80:95], v[8:11], v[104:107], v[80:95]
	v_add_f32_e32 v4, v32, v50
	v_cvt_pk_bf16_f32 v120, v50, v52
	v_cvt_pk_bf16_f32 v121, v54, v56
	v_add_f32_e32 v4, v4, v52
	v_add_f32_e32 v4, v4, v54
	v_add_f32_e32 v4, v4, v56
	s_waitcnt lgkmcnt(4)
	v_mfma_f32_32x32x16_bf16 v[64:79], v[12:15], v[104:107], v[64:79]
	v_add_f32_e32 v4, v4, v58
	v_cvt_pk_bf16_f32 v122, v58, v60
	v_cvt_pk_bf16_f32 v123, v62, v112
	v_add_f32_e32 v4, v4, v60
	v_add_f32_e32 v4, v4, v62
	v_add_f32_e32 v4, v4, v112
	s_waitcnt lgkmcnt(3)
	v_mfma_f32_32x32x16_bf16 v[80:95], v[16:19], v[100:103], v[80:95]
	v_add_f32_e32 v4, v4, v35
	v_cvt_pk_bf16_f32 v116, v35, v37
	v_cvt_pk_bf16_f32 v117, v39, v41
	v_add_f32_e32 v4, v4, v37
	v_add_f32_e32 v4, v4, v39
	v_add_f32_e32 v4, v4, v41
	s_waitcnt lgkmcnt(2)
	v_mfma_f32_32x32x16_bf16 v[64:79], v[20:23], v[100:103], v[64:79]
	v_add_f32_e32 v4, v4, v43
	v_cvt_pk_bf16_f32 v118, v43, v45
	v_cvt_pk_bf16_f32 v119, v47, v49
	v_add_f32_e32 v4, v4, v45
	v_add_f32_e32 v4, v4, v47
	v_add_f32_e32 v12, v4, v49
	v_add_u32_e32 v137, 0, v138
	v_add_u32_e32 v136, 0, v139
	ds_read_b64_tr_b16 v[4:5], v137
	ds_read_b64_tr_b16 v[6:7], v136
	ds_read_b64_tr_b16 v[10:11], v136 offset:512
	ds_read_b64_tr_b16 v[8:9], v137 offset:512
	s_waitcnt lgkmcnt(5)
	v_mfma_f32_32x32x16_bf16 v[80:95], v[24:27], v[96:99], v[80:95]
	v_add_f32_e32 v12, v12, v51
	v_cvt_pk_bf16_f32 v112, v51, v53
	v_cvt_pk_bf16_f32 v113, v55, v57
	v_add_f32_e32 v12, v12, v53
	v_add_f32_e32 v12, v12, v55
	v_add_f32_e32 v12, v12, v57
	s_waitcnt lgkmcnt(4)
	v_mfma_f32_32x32x16_bf16 v[64:79], v[28:31], v[96:99], v[64:79]
	v_add_f32_e32 v12, v12, v59
	v_cvt_pk_bf16_f32 v114, v59, v61
	v_add_f32_e32 v12, v12, v61
	v_add_f32_e32 v12, v12, v63
	v_add_f32_e32 v12, v12, v115
	v_cvt_pk_bf16_f32 v115, v63, v115
	s_add_i32 s0, s53, 0x18000
	s_add_u32 s26, s14, 0x8000
	s_addc_u32 s27, s15, 0
	s_mov_b32 s1, m0
	s_mov_b32 m0, s0
	s_nop 0
	global_load_lds_dwordx4 v141, s[26:27]
	s_mov_b32 m0, s1
	s_add_u32 s26, s14, 0xa000
	s_addc_u32 s27, s15, 0
	s_add_i32 s53, s53, 0x1a000
	s_mov_b32 s0, m0
	s_mov_b32 m0, s53
	s_nop 0
	global_load_lds_dwordx4 v141, s[26:27]
	s_mov_b32 m0, s0
	v_add_f32_e32 v154, 0, v12
	s_waitcnt lgkmcnt(2)
	v_mfma_f32_32x32x16_bf16 v[48:63], v[4:7], v[0:3], 0
	ds_read_b64_tr_b16 v[12:13], v137 offset:1024
	ds_read_b64_tr_b16 v[14:15], v136 offset:1024
	v_exp_f32_e32 v155, v80
	v_exp_f32_e32 v156, v81
	s_waitcnt lgkmcnt(2)
	v_mfma_f32_32x32x16_bf16 v[32:47], v[8:11], v[0:3], 0
	ds_read_b64_tr_b16 v[4:5], v137 offset:1536
	ds_read_b64_tr_b16 v[6:7], v136 offset:1536
	v_exp_f32_e32 v157, v82
	v_exp_f32_e32 v158, v83
	s_waitcnt lgkmcnt(2)
	v_mfma_f32_32x32x16_bf16 v[16:31], v[12:15], v[0:3], 0
	ds_read_b64_tr_b16 v[80:81], v137 offset:4096
	ds_read_b64_tr_b16 v[82:83], v136 offset:4096
	v_exp_f32_e32 v159, v84
	v_exp_f32_e32 v160, v85
	s_waitcnt lgkmcnt(2)
	v_mfma_f32_32x32x16_bf16 v[0:15], v[4:7], v[0:3], 0
	ds_read_b64_tr_b16 v[132:133], v137 offset:4608
	ds_read_b64_tr_b16 v[134:135], v136 offset:4608
	v_exp_f32_e32 v161, v86
	v_exp_f32_e32 v162, v87
	ds_read_b128 v[84:87], v140 offset:32768
	ds_read_b128 v[128:131], v140 offset:33280
	s_waitcnt lgkmcnt(4)
	v_mfma_f32_32x32x16_bf16 v[48:63], v[80:83], v[120:123], v[48:63]
	ds_read_b64_tr_b16 v[142:143], v137 offset:5120
	ds_read_b64_tr_b16 v[144:145], v136 offset:5120
	v_exp_f32_e32 v163, v88
	v_exp_f32_e32 v164, v89
	ds_read_b128 v[146:149], v140 offset:34816
	ds_read_b128 v[124:127], v140 offset:35328
	s_waitcnt lgkmcnt(6)
	v_mfma_f32_32x32x16_bf16 v[32:47], v[132:135], v[120:123], v[32:47]
	ds_read_b64_tr_b16 v[80:81], v137 offset:5632
	ds_read_b64_tr_b16 v[82:83], v136 offset:5632
	v_exp_f32_e32 v165, v90
	v_exp_f32_e32 v166, v91
	s_waitcnt lgkmcnt(4)
	v_mfma_f32_32x32x16_bf16 v[16:31], v[142:145], v[120:123], v[16:31]
	ds_read_b64_tr_b16 v[88:89], v137 offset:8192
	ds_read_b64_tr_b16 v[90:91], v136 offset:8192
	v_exp_f32_e32 v167, v92
	v_exp_f32_e32 v170, v93
	s_waitcnt lgkmcnt(2)
	v_mfma_f32_32x32x16_bf16 v[0:15], v[80:83], v[120:123], v[0:15]
	ds_read_b64_tr_b16 v[132:133], v137 offset:8704
	ds_read_b64_tr_b16 v[134:135], v136 offset:8704
	v_exp_f32_e32 v123, v94
	v_exp_f32_e32 v171, v95
	s_waitcnt lgkmcnt(2)
	v_mfma_f32_32x32x16_bf16 v[48:63], v[88:91], v[116:119], v[48:63]
	ds_read_b64_tr_b16 v[80:81], v137 offset:9216
	ds_read_b64_tr_b16 v[82:83], v136 offset:9216
	v_exp_f32_e32 v172, v64
	v_exp_f32_e32 v173, v65
	s_waitcnt lgkmcnt(2)
	v_mfma_f32_32x32x16_bf16 v[32:47], v[132:135], v[116:119], v[32:47]
	ds_read_b64_tr_b16 v[88:89], v137 offset:9728
	ds_read_b64_tr_b16 v[90:91], v136 offset:9728
	v_exp_f32_e32 v174, v66
	v_exp_f32_e32 v175, v67
	s_waitcnt lgkmcnt(2)
	v_mfma_f32_32x32x16_bf16 v[16:31], v[80:83], v[116:119], v[16:31]
	ds_read_b64_tr_b16 v[64:65], v137 offset:12288
	ds_read_b64_tr_b16 v[66:67], v136 offset:12288
	v_exp_f32_e32 v176, v68
	v_exp_f32_e32 v182, v69
	s_waitcnt lgkmcnt(2)
	v_mfma_f32_32x32x16_bf16 v[0:15], v[88:91], v[116:119], v[0:15]
	ds_read_b64_tr_b16 v[80:81], v137 offset:12800
	ds_read_b64_tr_b16 v[82:83], v136 offset:12800
	v_exp_f32_e32 v183, v70
	v_exp_f32_e32 v184, v71
	s_waitcnt lgkmcnt(2)
	v_mfma_f32_32x32x16_bf16 v[48:63], v[64:67], v[112:115], v[48:63]
	ds_read_b64_tr_b16 v[68:69], v137 offset:13312
	ds_read_b64_tr_b16 v[70:71], v136 offset:13312
	v_exp_f32_e32 v185, v72
	v_exp_f32_e32 v186, v73
	s_waitcnt lgkmcnt(2)
	v_mfma_f32_32x32x16_bf16 v[32:47], v[80:83], v[112:115], v[32:47]
	ds_read_b64_tr_b16 v[64:65], v137 offset:13824
	ds_read_b64_tr_b16 v[66:67], v136 offset:13824
	v_exp_f32_e32 v187, v74
	v_exp_f32_e32 v188, v75
	s_waitcnt lgkmcnt(2)
	v_mfma_f32_32x32x16_bf16 v[16:31], v[68:71], v[112:115], v[16:31]
	v_exp_f32_e32 v189, v76
	v_exp_f32_e32 v190, v77
	s_waitcnt lgkmcnt(0)
	v_mfma_f32_32x32x16_bf16 v[0:15], v[64:67], v[112:115], v[0:15]
	v_exp_f32_e32 v191, v78
	v_exp_f32_e32 v192, v79
	s_waitcnt vmcnt(2) lgkmcnt(0)
	s_barrier
; #define AT_WAIT_BAR(N) asm volatile("s_waitcnt vmcnt(" #N ") lgkmcnt(0)\n\ts_barrier" ::: "memory")
; #define AT_ROT() do { sl_prev = sl_cur; sl_cur = sl_next; sl_next = (sl_next == 2) ? 0 : sl_next + 1; } while (0)
; #define AT_ENDW(tt) do { if ((tt) + 3 < NT) { AT_WAIT_BAR(4); } else if ((tt) + 2 < NT) { AT_WAIT_BAR(2); } else { AT_WAIT_BAR(0); } } while (0)
; __device__ __forceinline__ void attn_unit(LAS unsigned char* lds, const bf16_t* Qb, const bf16_t* Kb, const bf16_t* Vb, bf16_t* mix,
;                                           int b, int head, int qbase  , float lam, float post_scale, const float* subg) {
;     ...
;     int t = 1;
;     for (; t + 5 < NT; t += 2) {
;         AT_STEP(pB0, pB1, pA0, pA1, t, true, true, true);     AT_WAIT_BAR(4); AT_ROT();
;         AT_STEP(pA0, pA1, pB0, pB1, t + 1, true, true, true); AT_WAIT_BAR(4); AT_ROT();
;     }
;     for (; t + 1 < NT; t += 2) {
;         AT_STEP(pB0, pB1, pA0, pA1, t, (t + 3 < NT), (t + 1 < NT), (t + 1 < NT));         AT_ENDW(t);     AT_ROT();
;         AT_STEP(pA0, pA1, pB0, pB1, t + 1, (t + 4 < NT), (t + 2 < NT), (t + 2 < NT));     AT_ENDW(t + 1); AT_ROT();
	ds_read_b128 v[112:115], v140 offset:36864
	ds_read_b128 v[116:119], v140 offset:37376
	ds_read_b128 v[142:145], v140 offset:38912
	ds_read_b128 v[150:153], v140 offset:39424
	v_mfma_f32_32x32x16_bf16 v[80:95], v[84:87], v[108:111], 0
	v_add_f32_e32 v64, v177, v155
	v_cvt_pk_bf16_f32 v132, v155, v156
	v_cvt_pk_bf16_f32 v133, v157, v158
	v_add_f32_e32 v64, v64, v156
	v_add_f32_e32 v64, v64, v157
	v_add_f32_e32 v64, v64, v158
	v_add_f32_e32 v64, v64, v159
	v_cvt_pk_bf16_f32 v134, v159, v160
	v_cvt_pk_bf16_f32 v135, v161, v162
	v_add_f32_e32 v64, v64, v160
	v_add_f32_e32 v64, v64, v161
	v_add_f32_e32 v120, v64, v162
	v_mfma_f32_32x32x16_bf16 v[64:79], v[128:131], v[108:111], 0
	v_mfma_f32_32x32x16_bf16 v[80:95], v[146:149], v[104:107], v[80:95]
	v_add_f32_e32 v120, v120, v163
	v_add_f32_e32 v120, v120, v164
	v_add_f32_e32 v120, v120, v165
	v_add_f32_e32 v122, v120, v166
	v_cvt_pk_bf16_f32 v120, v163, v164
	v_cvt_pk_bf16_f32 v121, v165, v166
	v_mfma_f32_32x32x16_bf16 v[64:79], v[124:127], v[104:107], v[64:79]
	v_add_f32_e32 v122, v122, v167
	v_add_f32_e32 v122, v122, v170
	v_add_f32_e32 v122, v122, v123
	v_add_f32_e32 v124, v122, v171
	v_cvt_pk_bf16_f32 v122, v167, v170
	v_cvt_pk_bf16_f32 v123, v123, v171
	s_waitcnt lgkmcnt(3)
	v_mfma_f32_32x32x16_bf16 v[80:95], v[112:115], v[100:103], v[80:95]
	v_add_f32_e32 v112, v124, v172
	v_add_f32_e32 v112, v112, v173
	v_add_f32_e32 v112, v112, v174
	v_add_f32_e32 v114, v112, v175
	v_cvt_pk_bf16_f32 v112, v172, v173
	v_cvt_pk_bf16_f32 v113, v174, v175
	s_waitcnt lgkmcnt(2)
	v_mfma_f32_32x32x16_bf16 v[64:79], v[116:119], v[100:103], v[64:79]
	v_add_f32_e32 v114, v114, v176
	v_add_f32_e32 v114, v114, v182
	v_add_f32_e32 v114, v114, v183
	v_add_f32_e32 v116, v114, v184
	v_cvt_pk_bf16_f32 v114, v176, v182
	v_cvt_pk_bf16_f32 v115, v183, v184
	v_add_u32_e32 v129, s52, v138
	v_add_u32_e32 v155, s52, v139
	ds_read_b64_tr_b16 v[124:125], v129
	ds_read_b64_tr_b16 v[126:127], v155
	ds_read_b64_tr_b16 v[148:149], v155 offset:512
	ds_read_b64_tr_b16 v[146:147], v129 offset:512
	s_waitcnt lgkmcnt(5)
	v_mfma_f32_32x32x16_bf16 v[80:95], v[142:145], v[96:99], v[80:95]
	v_add_f32_e32 v116, v116, v185
	v_add_f32_e32 v116, v116, v186
	v_add_f32_e32 v116, v116, v187
	v_add_f32_e32 v118, v116, v188
	v_cvt_pk_bf16_f32 v116, v185, v186
	v_cvt_pk_bf16_f32 v117, v187, v188
	s_waitcnt lgkmcnt(4)
	v_mfma_f32_32x32x16_bf16 v[64:79], v[150:153], v[96:99], v[64:79]
	v_add_f32_e32 v118, v118, v189
	v_add_f32_e32 v118, v118, v190
	v_add_f32_e32 v118, v118, v191
	v_add_f32_e32 v128, v118, v192
	v_cvt_pk_bf16_f32 v118, v189, v190
	v_cvt_pk_bf16_f32 v119, v191, v192
	s_add_u32 s26, s14, 0xc000
	s_addc_u32 s27, s15, 0
	s_mov_b32 s0, m0
	s_mov_b32 m0, s49
	s_nop 0
	global_load_lds_dwordx4 v141, s[26:27]
	s_mov_b32 m0, s0
	s_add_u32 s14, s14, 0xe000
	s_addc_u32 s15, s15, 0
	s_mov_b32 s0, m0
	s_mov_b32 m0, s51
	s_nop 0
	global_load_lds_dwordx4 v141, s[14:15]
	s_mov_b32 m0, s0
	v_add_f32_e32 v128, v154, v128
	s_waitcnt lgkmcnt(2)
	v_mfma_f32_32x32x16_bf16 v[48:63], v[124:127], v[132:135], v[48:63]
	ds_read_b64_tr_b16 v[142:143], v129 offset:1024
	ds_read_b64_tr_b16 v[144:145], v155 offset:1024
	v_exp_f32_e32 v154, v80
	v_exp_f32_e32 v156, v81
	s_waitcnt lgkmcnt(2)
	v_mfma_f32_32x32x16_bf16 v[32:47], v[146:149], v[132:135], v[32:47]
	ds_read_b64_tr_b16 v[124:125], v129 offset:1536
	ds_read_b64_tr_b16 v[126:127], v155 offset:1536
	v_exp_f32_e32 v157, v82
	v_exp_f32_e32 v158, v83
	s_waitcnt lgkmcnt(2)
	v_mfma_f32_32x32x16_bf16 v[16:31], v[142:145], v[132:135], v[16:31]
	ds_read_b64_tr_b16 v[80:81], v129 offset:4096
	ds_read_b64_tr_b16 v[82:83], v155 offset:4096
	v_exp_f32_e32 v159, v84
	v_exp_f32_e32 v160, v85
	s_waitcnt lgkmcnt(2)
	v_mfma_f32_32x32x16_bf16 v[0:15], v[124:127], v[132:135], v[0:15]
	ds_read_b64_tr_b16 v[142:143], v129 offset:4608
	ds_read_b64_tr_b16 v[144:145], v155 offset:4608
	v_exp_f32_e32 v134, v86
	v_exp_f32_e32 v135, v87
	ds_read_b128 v[84:87], v140 offset:49152
	ds_read_b128 v[130:133], v140 offset:49664
	s_waitcnt lgkmcnt(4)
	v_mfma_f32_32x32x16_bf16 v[48:63], v[80:83], v[120:123], v[48:63]
	ds_read_b64_tr_b16 v[146:147], v129 offset:5120
	ds_read_b64_tr_b16 v[148:149], v155 offset:5120
	v_exp_f32_e32 v161, v88
	v_exp_f32_e32 v162, v89
	ds_read_b128 v[150:153], v140 offset:51200
	ds_read_b128 v[124:127], v140 offset:51712
	s_waitcnt lgkmcnt(6)
	v_mfma_f32_32x32x16_bf16 v[32:47], v[142:145], v[120:123], v[32:47]
	ds_read_b64_tr_b16 v[80:81], v129 offset:5632
	ds_read_b64_tr_b16 v[82:83], v155 offset:5632
	v_exp_f32_e32 v163, v90
	v_exp_f32_e32 v164, v91
	s_waitcnt lgkmcnt(4)
	v_mfma_f32_32x32x16_bf16 v[16:31], v[146:149], v[120:123], v[16:31]
	ds_read_b64_tr_b16 v[88:89], v129 offset:8192
	ds_read_b64_tr_b16 v[90:91], v155 offset:8192
	v_exp_f32_e32 v148, v92
	v_exp_f32_e32 v149, v93
	s_waitcnt lgkmcnt(2)
	v_mfma_f32_32x32x16_bf16 v[0:15], v[80:83], v[120:123], v[0:15]
	ds_read_b64_tr_b16 v[142:143], v129 offset:8704
	ds_read_b64_tr_b16 v[144:145], v155 offset:8704
	v_exp_f32_e32 v165, v94
	v_exp_f32_e32 v166, v95
	s_waitcnt lgkmcnt(2)
	v_mfma_f32_32x32x16_bf16 v[48:63], v[88:91], v[112:115], v[48:63]
	ds_read_b64_tr_b16 v[80:81], v129 offset:9216
	ds_read_b64_tr_b16 v[82:83], v155 offset:9216
	v_exp_f32_e32 v167, v64
	v_exp_f32_e32 v170, v65
	s_waitcnt lgkmcnt(2)
	v_mfma_f32_32x32x16_bf16 v[32:47], v[142:145], v[112:115], v[32:47]
	ds_read_b64_tr_b16 v[88:89], v129 offset:9728
	ds_read_b64_tr_b16 v[90:91], v155 offset:9728
	v_exp_f32_e32 v171, v66
	v_exp_f32_e32 v172, v67
	s_waitcnt lgkmcnt(2)
	v_mfma_f32_32x32x16_bf16 v[16:31], v[80:83], v[112:115], v[16:31]
	ds_read_b64_tr_b16 v[64:65], v129 offset:12288
	ds_read_b64_tr_b16 v[66:67], v155 offset:12288
	v_exp_f32_e32 v173, v68
	v_exp_f32_e32 v174, v69
	s_waitcnt lgkmcnt(2)
	v_mfma_f32_32x32x16_bf16 v[0:15], v[88:91], v[112:115], v[0:15]
	ds_read_b64_tr_b16 v[80:81], v129 offset:12800
	ds_read_b64_tr_b16 v[82:83], v155 offset:12800
	v_exp_f32_e32 v175, v70
	v_exp_f32_e32 v176, v71
	s_waitcnt lgkmcnt(2)
	v_mfma_f32_32x32x16_bf16 v[48:63], v[64:67], v[116:119], v[48:63]
	ds_read_b64_tr_b16 v[68:69], v129 offset:13312
	ds_read_b64_tr_b16 v[70:71], v155 offset:13312
	v_exp_f32_e32 v182, v72
	v_exp_f32_e32 v183, v73
	s_waitcnt lgkmcnt(2)
	v_mfma_f32_32x32x16_bf16 v[32:47], v[80:83], v[116:119], v[32:47]
	ds_read_b64_tr_b16 v[64:65], v129 offset:13824
	ds_read_b64_tr_b16 v[66:67], v155 offset:13824
	v_exp_f32_e32 v129, v74
	v_exp_f32_e32 v155, v75
	s_waitcnt lgkmcnt(2)
	v_mfma_f32_32x32x16_bf16 v[16:31], v[68:71], v[116:119], v[16:31]
	v_exp_f32_e32 v184, v76
	v_exp_f32_e32 v185, v77
	s_waitcnt lgkmcnt(0)
	v_mfma_f32_32x32x16_bf16 v[0:15], v[64:67], v[116:119], v[0:15]
	v_exp_f32_e32 v186, v78
	v_exp_f32_e32 v187, v79
	s_waitcnt vmcnt(0) lgkmcnt(0)
	s_barrier
; #define AT_WAIT_BAR(N) asm volatile("s_waitcnt vmcnt(" #N ") lgkmcnt(0)\n\ts_barrier" ::: "memory")
; #define AT_ROT() do { sl_prev = sl_cur; sl_cur = sl_next; sl_next = (sl_next == 2) ? 0 : sl_next + 1; } while (0)
; #define AT_ENDW(tt) do { if ((tt) + 3 < NT) { AT_WAIT_BAR(4); } else if ((tt) + 2 < NT) { AT_WAIT_BAR(2); } else { AT_WAIT_BAR(0); } } while (0)
; __device__ __forceinline__ void attn_unit(LAS unsigned char* lds, const bf16_t* Qb, const bf16_t* Kb, const bf16_t* Vb, bf16_t* mix,
;                                           int b, int head, int qbase  , float lam, float post_scale, const float* subg) {
;     ...
;     int t = 1;
;     for (; t + 5 < NT; t += 2) {
;         AT_STEP(pB0, pB1, pA0, pA1, t, true, true, true);     AT_WAIT_BAR(4); AT_ROT();
;         AT_STEP(pA0, pA1, pB0, pB1, t + 1, true, true, true); AT_WAIT_BAR(4); AT_ROT();
;     }
;     for (; t + 1 < NT; t += 2) {
;         AT_STEP(pB0, pB1, pA0, pA1, t, (t + 3 < NT), (t + 1 < NT), (t + 1 < NT));         AT_ENDW(t);     AT_ROT();
;         AT_STEP(pA0, pA1, pB0, pB1, t + 1, (t + 4 < NT), (t + 2 < NT), (t + 2 < NT));     AT_ENDW(t + 1); AT_ROT();
;     }
;     AT_STEP(pB0, pB1, pA0, pA1, NT - 1, false, false, false);
	ds_read_b128 v[112:115], v140 offset:53248
	ds_read_b128 v[116:119], v140 offset:53760
	ds_read_b128 v[120:123], v140 offset:55296
	ds_read_b128 v[140:143], v140 offset:55808
	v_mfma_f32_32x32x16_bf16 v[80:95], v[84:87], v[108:111], 0
	v_add_f32_e32 v64, v177, v154
	v_cvt_pk_bf16_f32 v144, v154, v156
	v_cvt_pk_bf16_f32 v145, v157, v158
	v_add_f32_e32 v64, v64, v156
	v_add_f32_e32 v64, v64, v157
	v_add_f32_e32 v64, v64, v158
	v_add_f32_e32 v64, v64, v159
	v_cvt_pk_bf16_f32 v146, v159, v160
	v_cvt_pk_bf16_f32 v147, v134, v135
	v_add_f32_e32 v64, v64, v160
	v_add_f32_e32 v64, v64, v134
	v_add_f32_e32 v154, v64, v135
	v_mfma_f32_32x32x16_bf16 v[64:79], v[130:133], v[108:111], 0
	v_mfma_f32_32x32x16_bf16 v[80:95], v[150:153], v[104:107], v[80:95]
	v_add_f32_e32 v108, v154, v161
	v_add_f32_e32 v108, v108, v162
	v_add_f32_e32 v108, v108, v163
	v_add_f32_e32 v110, v108, v164
	v_cvt_pk_bf16_f32 v108, v161, v162
	v_cvt_pk_bf16_f32 v109, v163, v164
	v_mfma_f32_32x32x16_bf16 v[64:79], v[124:127], v[104:107], v[64:79]
	v_add_f32_e32 v104, v110, v148
	v_cvt_pk_bf16_f32 v110, v148, v149
	v_cvt_pk_bf16_f32 v111, v165, v166
	v_add_f32_e32 v104, v104, v149
	v_add_f32_e32 v104, v104, v165
	v_add_f32_e32 v104, v104, v166
	s_waitcnt lgkmcnt(3)
	v_mfma_f32_32x32x16_bf16 v[80:95], v[112:115], v[100:103], v[80:95]
	v_add_f32_e32 v104, v104, v167
	v_add_f32_e32 v104, v104, v170
	v_add_f32_e32 v104, v104, v171
	v_add_f32_e32 v106, v104, v172
	v_cvt_pk_bf16_f32 v104, v167, v170
	v_cvt_pk_bf16_f32 v105, v171, v172
	s_waitcnt lgkmcnt(2)
	v_mfma_f32_32x32x16_bf16 v[64:79], v[116:119], v[100:103], v[64:79]
	v_add_f32_e32 v100, v106, v173
	v_cvt_pk_bf16_f32 v106, v173, v174
	v_cvt_pk_bf16_f32 v107, v175, v176
	v_add_f32_e32 v100, v100, v174
	v_add_f32_e32 v100, v100, v175
	v_add_f32_e32 v100, v100, v176
	v_add_u32_e32 v124, s46, v138
	v_add_u32_e32 v125, s46, v139
	ds_read_b64_tr_b16 v[112:113], v124
	ds_read_b64_tr_b16 v[114:115], v125
	ds_read_b64_tr_b16 v[118:119], v125 offset:512
	ds_read_b64_tr_b16 v[116:117], v124 offset:512
	s_waitcnt lgkmcnt(5)
	v_mfma_f32_32x32x16_bf16 v[80:95], v[120:123], v[96:99], v[80:95]
	v_add_f32_e32 v100, v100, v182
	v_add_f32_e32 v100, v100, v183
	v_add_f32_e32 v100, v100, v129
	v_add_f32_e32 v102, v100, v155
	v_cvt_pk_bf16_f32 v100, v182, v183
	v_cvt_pk_bf16_f32 v101, v129, v155
	s_waitcnt lgkmcnt(4)
	v_mfma_f32_32x32x16_bf16 v[64:79], v[140:143], v[96:99], v[64:79]
	v_add_f32_e32 v96, v102, v184
	v_cvt_pk_bf16_f32 v102, v184, v185
	v_cvt_pk_bf16_f32 v103, v186, v187
	v_add_f32_e32 v96, v96, v185
	v_add_f32_e32 v96, v96, v186
	s_nop 0
	v_add_f32_e32 v120, v96, v187
	s_waitcnt lgkmcnt(2)
	v_mfma_f32_32x32x16_bf16 v[48:63], v[112:115], v[144:147], v[48:63]
	ds_read_b64_tr_b16 v[96:97], v124 offset:1024
	ds_read_b64_tr_b16 v[98:99], v125 offset:1024
	v_exp_f32_e32 v121, v80
	v_exp_f32_e32 v122, v81
	s_waitcnt lgkmcnt(2)
	v_mfma_f32_32x32x16_bf16 v[32:47], v[116:119], v[144:147], v[32:47]
	ds_read_b64_tr_b16 v[112:113], v124 offset:1536
	ds_read_b64_tr_b16 v[114:115], v125 offset:1536
	v_exp_f32_e32 v116, v82
	v_exp_f32_e32 v117, v83
	s_waitcnt lgkmcnt(2)
	v_mfma_f32_32x32x16_bf16 v[16:31], v[96:99], v[144:147], v[16:31]
	ds_read_b64_tr_b16 v[80:81], v124 offset:4096
	ds_read_b64_tr_b16 v[82:83], v125 offset:4096
	v_exp_f32_e32 v118, v84
	v_exp_f32_e32 v119, v85
	s_waitcnt lgkmcnt(2)
	v_mfma_f32_32x32x16_bf16 v[0:15], v[112:115], v[144:147], v[0:15]
	ds_read_b64_tr_b16 v[96:97], v124 offset:4608
	ds_read_b64_tr_b16 v[98:99], v125 offset:4608
	v_exp_f32_e32 v112, v86
	v_exp_f32_e32 v113, v87
	s_waitcnt lgkmcnt(2)
	v_mfma_f32_32x32x16_bf16 v[48:63], v[80:83], v[108:111], v[48:63]
	ds_read_b64_tr_b16 v[84:85], v124 offset:5120
	ds_read_b64_tr_b16 v[86:87], v125 offset:5120
	v_exp_f32_e32 v114, v88
	v_exp_f32_e32 v115, v89
	s_waitcnt lgkmcnt(2)
	v_mfma_f32_32x32x16_bf16 v[32:47], v[96:99], v[108:111], v[32:47]
	ds_read_b64_tr_b16 v[80:81], v124 offset:5632
	ds_read_b64_tr_b16 v[82:83], v125 offset:5632
	v_exp_f32_e32 v96, v90
	v_exp_f32_e32 v97, v91
	s_waitcnt lgkmcnt(2)
	v_mfma_f32_32x32x16_bf16 v[16:31], v[84:87], v[108:111], v[16:31]
	ds_read_b64_tr_b16 v[88:89], v124 offset:8192
	ds_read_b64_tr_b16 v[90:91], v125 offset:8192
	v_exp_f32_e32 v92, v92
	v_exp_f32_e32 v93, v93
	s_waitcnt lgkmcnt(2)
	v_mfma_f32_32x32x16_bf16 v[0:15], v[80:83], v[108:111], v[0:15]
	ds_read_b64_tr_b16 v[84:85], v124 offset:8704
	ds_read_b64_tr_b16 v[86:87], v125 offset:8704
	v_exp_f32_e32 v94, v94
	v_exp_f32_e32 v95, v95
	s_waitcnt lgkmcnt(2)
	v_mfma_f32_32x32x16_bf16 v[48:63], v[88:91], v[104:107], v[48:63]
	ds_read_b64_tr_b16 v[80:81], v124 offset:9216
	ds_read_b64_tr_b16 v[82:83], v125 offset:9216
	v_exp_f32_e32 v98, v64
	v_exp_f32_e32 v99, v65
	s_waitcnt lgkmcnt(2)
	v_mfma_f32_32x32x16_bf16 v[32:47], v[84:87], v[104:107], v[32:47]
	ds_read_b64_tr_b16 v[88:89], v124 offset:9728
	ds_read_b64_tr_b16 v[90:91], v125 offset:9728
	v_exp_f32_e32 v84, v66
	v_exp_f32_e32 v85, v67
	s_waitcnt lgkmcnt(2)
	v_mfma_f32_32x32x16_bf16 v[16:31], v[80:83], v[104:107], v[16:31]
	ds_read_b64_tr_b16 v[64:65], v124 offset:12288
	ds_read_b64_tr_b16 v[66:67], v125 offset:12288
	v_exp_f32_e32 v86, v68
	v_exp_f32_e32 v87, v69
	s_waitcnt lgkmcnt(2)
	v_mfma_f32_32x32x16_bf16 v[0:15], v[88:91], v[104:107], v[0:15]
	ds_read_b64_tr_b16 v[80:81], v124 offset:12800
	ds_read_b64_tr_b16 v[82:83], v125 offset:12800
	v_exp_f32_e32 v88, v70
	v_exp_f32_e32 v89, v71
	s_waitcnt lgkmcnt(2)
	v_mfma_f32_32x32x16_bf16 v[48:63], v[64:67], v[100:103], v[48:63]
	ds_read_b64_tr_b16 v[68:69], v124 offset:13312
	ds_read_b64_tr_b16 v[70:71], v125 offset:13312
	v_exp_f32_e32 v90, v72
	v_exp_f32_e32 v91, v73
	s_waitcnt lgkmcnt(2)
; #define LAS __attribute__((address_space(3)))
; #define LAS __attribute__((address_space(3)))
; #define AT_VFRAG(dst, vp, n) do { const s16x4 lo_ = tr16((vp) + vlo + ((n) >> 2) * 4096 + ((n) & 3) * 512), hi_ = tr16((vp) + vhi + ((n) >> 2) * 4096 + ((n) & 3) * 512); \
;         dst = (bf16x8){lo_[0], lo_[1], lo_[2], lo_[3], hi_[0], hi_[1], hi_[2], hi_[3]}; } while (0)
; #define AT_PK(P, B) pkbf(P[B], P[B + 1])
; __device__ __forceinline__ void attn_unit(LAS unsigned char* lds, const bf16_t* Qb, const bf16_t* Kb, const bf16_t* Vb, bf16_t* mix,
;                                           int b, int head, int qbase  , float lam, float post_scale, const float* subg) {
;     ...
;     AT_STEP(pB0, pB1, pA0, pA1, NT - 1, false, false, false);
;     {
;         float sacc = 0.f;
; #pragma unroll
;         for (int i = 0; i < 16; ++i) sacc += pB0[i] + pB1[i];
;         lsum += sacc;
;         pw0 = (u32x4){AT_PK(pB0, 0), AT_PK(pB0, 2), AT_PK(pB0, 4), AT_PK(pB0, 6)}; pw1 = (u32x4){AT_PK(pB0, 8), AT_PK(pB0, 10), AT_PK(pB0, 12), AT_PK(pB0, 14)};
;         pw2 = (u32x4){AT_PK(pB1, 0), AT_PK(pB1, 2), AT_PK(pB1, 4), AT_PK(pB1, 6)}; pw3 = (u32x4){AT_PK(pB1, 8), AT_PK(pB1, 10), AT_PK(pB1, 12), AT_PK(pB1, 14)};
;         const u32x4 pwv[4] = {pw0, pw1, pw2, pw3};
;         const LAS unsigned char* vp_ = lds + sl_cur * 16384;
; #pragma unroll
;         for (int n = 0; n < 16; ++n) { bf16x8 vf_; AT_VFRAG(vf_, vp_, n); O[n & 3] = __builtin_amdgcn_mfma_f32_32x32x16_bf16(vf_, __builtin_bit_cast(bf16x8, pwv[n >> 2]), O[n & 3], 0, 0, 0); }
;     }
	v_mfma_f32_32x32x16_bf16 v[32:47], v[80:83], v[100:103], v[32:47]
	ds_read_b64_tr_b16 v[64:65], v124 offset:13824
	ds_read_b64_tr_b16 v[66:67], v125 offset:13824
	v_exp_f32_e32 v104, v74
	v_exp_f32_e32 v105, v75
	s_waitcnt lgkmcnt(2)
	v_mfma_f32_32x32x16_bf16 v[16:31], v[68:71], v[100:103], v[16:31]
	v_exp_f32_e32 v80, v76
	v_exp_f32_e32 v81, v77
	s_waitcnt lgkmcnt(0)
	v_mfma_f32_32x32x16_bf16 v[0:15], v[64:67], v[100:103], v[0:15]
	v_exp_f32_e32 v67, v78
	v_exp_f32_e32 v82, v79
	v_add_f32_e32 v125, v92, v80
	v_add_f32_e32 v126, v93, v81
	v_add_f32_e32 v127, v94, v67
	v_add_f32_e32 v129, v95, v82
	v_cvt_pk_bf16_f32 v72, v121, v122
	v_cvt_pk_bf16_f32 v73, v116, v117
	v_cvt_pk_bf16_f32 v74, v118, v119
	v_cvt_pk_bf16_f32 v75, v112, v113
	v_cvt_pk_bf16_f32 v76, v114, v115
	v_cvt_pk_bf16_f32 v77, v96, v97
	v_cvt_pk_bf16_f32 v78, v92, v93
	v_cvt_pk_bf16_f32 v79, v94, v95
	v_cvt_pk_bf16_f32 v68, v98, v99
	v_cvt_pk_bf16_f32 v69, v84, v85
	v_cvt_pk_bf16_f32 v70, v86, v87
	v_cvt_pk_bf16_f32 v71, v88, v89
	v_cvt_pk_bf16_f32 v64, v90, v91
	v_cvt_pk_bf16_f32 v65, v104, v105
	v_cvt_pk_bf16_f32 v66, v80, v81
	v_cvt_pk_bf16_f32 v67, v67, v82
	ds_read_b64_tr_b16 v[80:81], v137
	ds_read_b64_tr_b16 v[82:83], v136
	s_waitcnt lgkmcnt(0)
	v_mfma_f32_32x32x16_bf16 v[48:63], v[80:83], v[72:75], v[48:63]
	ds_read_b64_tr_b16 v[80:81], v137 offset:512
	ds_read_b64_tr_b16 v[82:83], v136 offset:512
	v_add_f32_e32 v100, v121, v98
	v_add_f32_e32 v101, v122, v99
	v_add_f32_e32 v102, v116, v84
	v_add_f32_e32 v103, v117, v85
	v_add_f32_e32 v106, v118, v86
	v_add_f32_e32 v107, v119, v87
	s_waitcnt lgkmcnt(0)
	v_mfma_f32_32x32x16_bf16 v[32:47], v[80:83], v[72:75], v[32:47]
	ds_read_b64_tr_b16 v[80:81], v137 offset:1024
	ds_read_b64_tr_b16 v[82:83], v136 offset:1024
	v_add_f32_e32 v108, v112, v88
	v_add_f32_e32 v109, v113, v89
	v_add_f32_e32 v110, v114, v90
	v_add_f32_e32 v111, v115, v91
	v_add_f32_e32 v123, v96, v104
	v_add_f32_e32 v124, v97, v105
	s_waitcnt lgkmcnt(0)
	v_mfma_f32_32x32x16_bf16 v[16:31], v[80:83], v[72:75], v[16:31]
	ds_read_b64_tr_b16 v[80:81], v137 offset:1536
	ds_read_b64_tr_b16 v[82:83], v136 offset:1536
	v_add_f32_e32 v120, v128, v120
	s_lshl_b32 s0, s45, 14
	s_add_i32 s0, s0, 0
	s_cmp_lg_u32 s44, 1
	s_waitcnt lgkmcnt(0)
	v_mfma_f32_32x32x16_bf16 v[0:15], v[80:83], v[72:75], v[0:15]
	ds_read_b64_tr_b16 v[72:73], v137 offset:4096
	ds_read_b64_tr_b16 v[74:75], v136 offset:4096
	s_waitcnt lgkmcnt(0)
	v_mfma_f32_32x32x16_bf16 v[48:63], v[72:75], v[76:79], v[48:63]
	ds_read_b64_tr_b16 v[72:73], v137 offset:4608
	ds_read_b64_tr_b16 v[74:75], v136 offset:4608
	s_waitcnt lgkmcnt(0)
	v_mfma_f32_32x32x16_bf16 v[32:47], v[72:75], v[76:79], v[32:47]
	ds_read_b64_tr_b16 v[72:73], v137 offset:5120
	ds_read_b64_tr_b16 v[74:75], v136 offset:5120
	s_waitcnt lgkmcnt(0)
	v_mfma_f32_32x32x16_bf16 v[16:31], v[72:75], v[76:79], v[16:31]
	ds_read_b64_tr_b16 v[72:73], v137 offset:5632
	ds_read_b64_tr_b16 v[74:75], v136 offset:5632
	s_waitcnt lgkmcnt(0)
	v_mfma_f32_32x32x16_bf16 v[0:15], v[72:75], v[76:79], v[0:15]
	ds_read_b64_tr_b16 v[72:73], v137 offset:8192
	ds_read_b64_tr_b16 v[74:75], v136 offset:8192
	s_waitcnt lgkmcnt(0)
	v_mfma_f32_32x32x16_bf16 v[48:63], v[72:75], v[68:71], v[48:63]
	ds_read_b64_tr_b16 v[72:73], v137 offset:8704
	ds_read_b64_tr_b16 v[74:75], v136 offset:8704
	s_waitcnt lgkmcnt(0)
	v_mfma_f32_32x32x16_bf16 v[32:47], v[72:75], v[68:71], v[32:47]
	ds_read_b64_tr_b16 v[72:73], v137 offset:9216
	ds_read_b64_tr_b16 v[74:75], v136 offset:9216
	s_waitcnt lgkmcnt(0)
	v_mfma_f32_32x32x16_bf16 v[16:31], v[72:75], v[68:71], v[16:31]
	ds_read_b64_tr_b16 v[72:73], v137 offset:9728
	ds_read_b64_tr_b16 v[74:75], v136 offset:9728
	s_waitcnt lgkmcnt(0)
	v_mfma_f32_32x32x16_bf16 v[0:15], v[72:75], v[68:71], v[0:15]
	ds_read_b64_tr_b16 v[68:69], v137 offset:12288
	ds_read_b64_tr_b16 v[70:71], v136 offset:12288
	s_waitcnt lgkmcnt(0)
	v_mfma_f32_32x32x16_bf16 v[48:63], v[68:71], v[64:67], v[48:63]
	ds_read_b64_tr_b16 v[68:69], v137 offset:12800
	ds_read_b64_tr_b16 v[70:71], v136 offset:12800
	s_waitcnt lgkmcnt(0)
	v_mfma_f32_32x32x16_bf16 v[32:47], v[68:71], v[64:67], v[32:47]
	ds_read_b64_tr_b16 v[68:69], v137 offset:13312
	ds_read_b64_tr_b16 v[70:71], v136 offset:13312
	s_waitcnt lgkmcnt(0)
	v_mfma_f32_32x32x16_bf16 v[16:31], v[68:71], v[64:67], v[16:31]
	ds_read_b64_tr_b16 v[68:69], v137 offset:13824
	ds_read_b64_tr_b16 v[70:71], v136 offset:13824
	s_waitcnt vmcnt(0) lgkmcnt(0)
	s_barrier
; #define LAS __attribute__((address_space(3)))
; #define LAS __attribute__((address_space(3)))
; __device__ __forceinline__ void attn_unit(LAS unsigned char* lds, const bf16_t* Qb, const bf16_t* Kb, const bf16_t* Vb, bf16_t* mix,
;                                           int b, int head, int qbase  , float lam, float post_scale, const float* subg) {
;     ...
;     asm volatile("s_waitcnt vmcnt(0) lgkmcnt(0)" ::: "memory");
;     __builtin_amdgcn_s_barrier();
;     asm volatile("" ::: "memory");
;     const float lt = lsum + __shfl_xor(lsum, 32);
;     int tid_e = threadIdx.x; asm volatile("" : "+v"(tid_e));
;     const int lane_e = tid_e & 63, h_e = lane_e >> 5, qidx_e = qbase + qg * 32 + (lane_e & 31);
;     LAS float* X = (LAS float*)lds + qg * 4096 + lane_e;
;     if (c == 1) {
;         const float sc = lam / lt;
; #pragma unroll
;         for (int d = 0; d < 4; ++d)
; #pragma unroll
;             for (int i = 0; i < 16; ++i) X[(d * 16 + i) * 64] = O[d][i] * sc;
;     }
	s_waitcnt lgkmcnt(0)
	v_mfma_f32_32x32x16_bf16 v[0:15], v[68:71], v[64:67], v[0:15]
	v_add_f32_e32 v64, 0, v100
	v_add_f32_e32 v64, v101, v64
	v_add_f32_e32 v64, v102, v64
	v_add_f32_e32 v64, v103, v64
	v_add_f32_e32 v64, v106, v64
	v_add_f32_e32 v64, v107, v64
	v_add_f32_e32 v64, v108, v64
	v_add_f32_e32 v64, v109, v64
	v_add_f32_e32 v64, v110, v64
	v_add_f32_e32 v64, v111, v64
	v_add_f32_e32 v64, v123, v64
	v_add_f32_e32 v64, v124, v64
	v_add_f32_e32 v64, v125, v64
	v_and_b32_e32 v66, 64, v229
	v_add_f32_e32 v64, v126, v64
	v_xor_b32_e32 v65, 32, v229
	v_add_u32_e32 v66, 64, v66
	v_add_f32_e32 v64, v127, v64
	v_cmp_lt_i32_e32 vcc, v65, v66
	v_add_f32_e32 v64, v129, v64
	v_add_f32_e32 v64, v120, v64
	v_cndmask_b32_e32 v65, v229, v65, vcc
	v_lshlrev_b32_e32 v79, 2, v65
	ds_bpermute_b32 v65, v79, v64
	v_mov_b32_e32 v67, v222
	s_waitcnt lgkmcnt(0)
	v_add_f32_e32 v64, v64, v65
	v_and_b32_e32 v65, 63, v67
	v_lshl_add_u32 v80, v65, 2, s0
	s_cbranch_scc1 .LBB0_422
	v_div_scale_f32 v65, s[14:15], v64, v64, v168
	v_rcp_f32_e32 v66, v65
	v_div_scale_f32 v68, vcc, v168, v64, v168
	v_fma_f32 v69, -v65, v66, 1.0
	v_fmac_f32_e32 v66, v69, v66
	v_mul_f32_e32 v69, v68, v66
	v_fma_f32 v70, -v65, v69, v68
	v_fmac_f32_e32 v69, v70, v66
	v_fma_f32 v65, -v65, v69, v68
	v_div_fmas_f32 v65, v65, v66, v69
	v_div_fixup_f32 v65, v65, v64, v168
	v_mul_f32_e32 v66, v48, v65
	v_mul_f32_e32 v68, v49, v65
	ds_write2st64_b32 v80, v66, v68 offset1:1
	v_mul_f32_e32 v66, v50, v65
	v_mul_f32_e32 v68, v51, v65
	ds_write2st64_b32 v80, v66, v68 offset0:2 offset1:3
	v_mul_f32_e32 v66, v52, v65
	v_mul_f32_e32 v68, v53, v65
	ds_write2st64_b32 v80, v66, v68 offset0:4 offset1:5
	v_mul_f32_e32 v66, v54, v65
	v_mul_f32_e32 v68, v55, v65
	ds_write2st64_b32 v80, v66, v68 offset0:6 offset1:7
	v_mul_f32_e32 v66, v56, v65
	v_mul_f32_e32 v68, v57, v65
	ds_write2st64_b32 v80, v66, v68 offset0:8 offset1:9
	v_mul_f32_e32 v66, v58, v65
	v_mul_f32_e32 v68, v59, v65
	ds_write2st64_b32 v80, v66, v68 offset0:10 offset1:11
	v_mul_f32_e32 v66, v60, v65
	v_mul_f32_e32 v68, v61, v65
	ds_write2st64_b32 v80, v66, v68 offset0:12 offset1:13
	v_mul_f32_e32 v66, v62, v65
	v_mul_f32_e32 v68, v63, v65
	ds_write2st64_b32 v80, v66, v68 offset0:14 offset1:15
	v_mul_f32_e32 v66, v32, v65
	v_mul_f32_e32 v68, v33, v65
	ds_write2st64_b32 v80, v66, v68 offset0:16 offset1:17
	v_mul_f32_e32 v66, v34, v65
	v_mul_f32_e32 v68, v35, v65
	ds_write2st64_b32 v80, v66, v68 offset0:18 offset1:19
	v_mul_f32_e32 v66, v36, v65
	v_mul_f32_e32 v68, v37, v65
	ds_write2st64_b32 v80, v66, v68 offset0:20 offset1:21
	v_mul_f32_e32 v66, v38, v65
	v_mul_f32_e32 v68, v39, v65
	ds_write2st64_b32 v80, v66, v68 offset0:22 offset1:23
	v_mul_f32_e32 v66, v40, v65
	v_mul_f32_e32 v68, v41, v65
	ds_write2st64_b32 v80, v66, v68 offset0:24 offset1:25
	v_mul_f32_e32 v66, v42, v65
	v_mul_f32_e32 v68, v43, v65
	ds_write2st64_b32 v80, v66, v68 offset0:26 offset1:27
	v_mul_f32_e32 v66, v44, v65
	v_mul_f32_e32 v68, v45, v65
	ds_write2st64_b32 v80, v66, v68 offset0:28 offset1:29
	v_mul_f32_e32 v66, v46, v65
	v_mul_f32_e32 v68, v47, v65
	ds_write2st64_b32 v80, v66, v68 offset0:30 offset1:31
	v_mul_f32_e32 v66, v16, v65
	v_mul_f32_e32 v68, v17, v65
	ds_write2st64_b32 v80, v66, v68 offset0:32 offset1:33
	v_mul_f32_e32 v66, v18, v65
	v_mul_f32_e32 v68, v19, v65
	ds_write2st64_b32 v80, v66, v68 offset0:34 offset1:35
	v_mul_f32_e32 v66, v20, v65
	v_mul_f32_e32 v68, v21, v65
	ds_write2st64_b32 v80, v66, v68 offset0:36 offset1:37
	v_mul_f32_e32 v66, v22, v65
	v_mul_f32_e32 v68, v23, v65
	ds_write2st64_b32 v80, v66, v68 offset0:38 offset1:39
	v_mul_f32_e32 v66, v24, v65
	v_mul_f32_e32 v68, v25, v65
	ds_write2st64_b32 v80, v66, v68 offset0:40 offset1:41
	v_mul_f32_e32 v66, v26, v65
	v_mul_f32_e32 v68, v27, v65
	ds_write2st64_b32 v80, v66, v68 offset0:42 offset1:43
	v_mul_f32_e32 v66, v28, v65
	v_mul_f32_e32 v68, v29, v65
	ds_write2st64_b32 v80, v66, v68 offset0:44 offset1:45
	v_mul_f32_e32 v66, v30, v65
	v_mul_f32_e32 v68, v31, v65
	ds_write2st64_b32 v80, v66, v68 offset0:46 offset1:47
	v_mul_f32_e32 v66, v0, v65
	v_mul_f32_e32 v68, v1, v65
	ds_write2st64_b32 v80, v66, v68 offset0:48 offset1:49
	v_mul_f32_e32 v66, v2, v65
	v_mul_f32_e32 v68, v3, v65
	ds_write2st64_b32 v80, v66, v68 offset0:50 offset1:51
	v_mul_f32_e32 v66, v4, v65
	v_mul_f32_e32 v68, v5, v65
	ds_write2st64_b32 v80, v66, v68 offset0:52 offset1:53
	v_mul_f32_e32 v66, v6, v65
	v_mul_f32_e32 v68, v7, v65
	ds_write2st64_b32 v80, v66, v68 offset0:54 offset1:55
	v_mul_f32_e32 v66, v8, v65
	v_mul_f32_e32 v68, v9, v65
	ds_write2st64_b32 v80, v66, v68 offset0:56 offset1:57
	v_mul_f32_e32 v66, v10, v65
	v_mul_f32_e32 v68, v11, v65
	ds_write2st64_b32 v80, v66, v68 offset0:58 offset1:59
	v_mul_f32_e32 v66, v12, v65
	v_mul_f32_e32 v68, v13, v65
	ds_write2st64_b32 v80, v66, v68 offset0:60 offset1:61
	v_mul_f32_e32 v66, v14, v65
	v_mul_f32_e32 v65, v15, v65
	ds_write2st64_b32 v80, v66, v65 offset0:62 offset1:63
